# P0 weight transposes: the 4-iteration row-load loops unrolled as a 2-deep software pipeline (16 loads in flight per wave, second register set); on top of DA/MLA attention restructure
# speedup vs baseline: 1.0107x; 1.0107x over previous
.LBB0_35:
	v_add_u32_e32 v63, s1, v4
	v_add_u32_e32 v14, 0xfcb20000, v63
	v_lshl_add_u64 v[6:7], v[14:15], 2, v[2:3]
	v_add_u32_e32 v14, 0xfcb21000, v63
	v_lshl_add_u64 v[8:9], v[14:15], 2, v[2:3]
	v_add_u32_e32 v14, 0xfcb22000, v63
	v_lshl_add_u64 v[10:11], v[14:15], 2, v[2:3]
	v_add_u32_e32 v14, 0xfcb23000, v63
	v_lshl_add_u64 v[12:13], v[14:15], 2, v[2:3]
	v_add_u32_e32 v14, 0xfcb24000, v63
	v_lshl_add_u64 v[64:65], v[14:15], 2, v[2:3]
	v_add_u32_e32 v14, 0xfcb25000, v63
	v_lshl_add_u64 v[66:67], v[14:15], 2, v[2:3]
	v_add_u32_e32 v14, 0xfcb26000, v63
	v_lshl_add_u64 v[68:69], v[14:15], 2, v[2:3]
	v_add_u32_e32 v14, 0xfcb27000, v63
	global_load_dwordx2 v[6:7], v[6:7], off
	s_nop 0
	global_load_dwordx2 v[8:9], v[8:9], off
	v_lshl_add_u64 v[70:71], v[14:15], 2, v[2:3]
	global_load_dwordx2 v[10:11], v[10:11], off
	s_nop 0
	global_load_dwordx2 v[12:13], v[12:13], off
	s_nop 0
	global_load_dwordx2 v[64:65], v[64:65], off
	s_nop 0
	global_load_dwordx2 v[66:67], v[66:67], off
	s_nop 0
	global_load_dwordx2 v[68:69], v[68:69], off
	s_nop 0
	global_load_dwordx2 v[70:71], v[70:71], off
	s_add_i32 s1, s1, 0x8000
	v_add_u32_e32 v63, s1, v4
	v_add_u32_e32 v14, 0xfcb20000, v63
	v_lshl_add_u64 v[200:201], v[14:15], 2, v[2:3]
	v_add_u32_e32 v14, 0xfcb21000, v63
	v_lshl_add_u64 v[202:203], v[14:15], 2, v[2:3]
	v_add_u32_e32 v14, 0xfcb22000, v63
	v_lshl_add_u64 v[204:205], v[14:15], 2, v[2:3]
	v_add_u32_e32 v14, 0xfcb23000, v63
	v_lshl_add_u64 v[206:207], v[14:15], 2, v[2:3]
	v_add_u32_e32 v14, 0xfcb24000, v63
	v_lshl_add_u64 v[208:209], v[14:15], 2, v[2:3]
	v_add_u32_e32 v14, 0xfcb25000, v63
	v_lshl_add_u64 v[210:211], v[14:15], 2, v[2:3]
	v_add_u32_e32 v14, 0xfcb26000, v63
	v_lshl_add_u64 v[212:213], v[14:15], 2, v[2:3]
	v_add_u32_e32 v14, 0xfcb27000, v63
	global_load_dwordx2 v[200:201], v[200:201], off
	s_nop 0
	global_load_dwordx2 v[202:203], v[202:203], off
	v_lshl_add_u64 v[214:215], v[14:15], 2, v[2:3]
	global_load_dwordx2 v[204:205], v[204:205], off
	s_nop 0
	global_load_dwordx2 v[206:207], v[206:207], off
	s_nop 0
	global_load_dwordx2 v[208:209], v[208:209], off
	s_nop 0
	global_load_dwordx2 v[210:211], v[210:211], off
	s_nop 0
	global_load_dwordx2 v[212:213], v[212:213], off
	s_nop 0
	global_load_dwordx2 v[214:215], v[214:215], off
	s_add_i32 s1, s1, 0x8000
	v_add_u32_e32 v14, 0x410, v5
	v_add_u32_e32 v63, 0x618, v5
	v_add_u32_e32 v72, 0x820, v5
	v_add_u32_e32 v73, 0xa28, v5
	v_add_u32_e32 v74, 0xc30, v5
	v_add_u32_e32 v75, 0xe38, v5
	s_waitcnt vmcnt(15)
	ds_write2_b32 v5, v6, v7 offset1:1
	s_waitcnt vmcnt(14)
	ds_write2_b32 v5, v8, v9 offset0:130 offset1:131
	v_add_u32_e32 v5, 0x1040, v5
	s_waitcnt vmcnt(13)
	ds_write2_b32 v14, v10, v11 offset1:1
	s_waitcnt vmcnt(12)
	ds_write2_b32 v63, v12, v13 offset1:1
	s_waitcnt vmcnt(11)
	ds_write2_b32 v72, v64, v65 offset1:1
	s_waitcnt vmcnt(10)
	ds_write2_b32 v73, v66, v67 offset1:1
	s_waitcnt vmcnt(9)
	ds_write2_b32 v74, v68, v69 offset1:1
	s_waitcnt vmcnt(8)
	ds_write2_b32 v75, v70, v71 offset1:1
	v_add_u32_e32 v63, s1, v4
	v_add_u32_e32 v14, 0xfcb20000, v63
	v_lshl_add_u64 v[6:7], v[14:15], 2, v[2:3]
	v_add_u32_e32 v14, 0xfcb21000, v63
	v_lshl_add_u64 v[8:9], v[14:15], 2, v[2:3]
	v_add_u32_e32 v14, 0xfcb22000, v63
	v_lshl_add_u64 v[10:11], v[14:15], 2, v[2:3]
	v_add_u32_e32 v14, 0xfcb23000, v63
	v_lshl_add_u64 v[12:13], v[14:15], 2, v[2:3]
	v_add_u32_e32 v14, 0xfcb24000, v63
	v_lshl_add_u64 v[64:65], v[14:15], 2, v[2:3]
	v_add_u32_e32 v14, 0xfcb25000, v63
	v_lshl_add_u64 v[66:67], v[14:15], 2, v[2:3]
	v_add_u32_e32 v14, 0xfcb26000, v63
	v_lshl_add_u64 v[68:69], v[14:15], 2, v[2:3]
	v_add_u32_e32 v14, 0xfcb27000, v63
	global_load_dwordx2 v[6:7], v[6:7], off
	s_nop 0
	global_load_dwordx2 v[8:9], v[8:9], off
	v_lshl_add_u64 v[70:71], v[14:15], 2, v[2:3]
	global_load_dwordx2 v[10:11], v[10:11], off
	s_nop 0
	global_load_dwordx2 v[12:13], v[12:13], off
	s_nop 0
	global_load_dwordx2 v[64:65], v[64:65], off
	s_nop 0
	global_load_dwordx2 v[66:67], v[66:67], off
	s_nop 0
	global_load_dwordx2 v[68:69], v[68:69], off
	s_nop 0
	global_load_dwordx2 v[70:71], v[70:71], off
	s_add_i32 s1, s1, 0x8000
	v_add_u32_e32 v14, 0x410, v5
	v_add_u32_e32 v63, 0x618, v5
	v_add_u32_e32 v72, 0x820, v5
	v_add_u32_e32 v73, 0xa28, v5
	v_add_u32_e32 v74, 0xc30, v5
	v_add_u32_e32 v75, 0xe38, v5
	s_waitcnt vmcnt(15)
	ds_write2_b32 v5, v200, v201 offset1:1
	s_waitcnt vmcnt(14)
	ds_write2_b32 v5, v202, v203 offset0:130 offset1:131
	v_add_u32_e32 v5, 0x1040, v5
	s_waitcnt vmcnt(13)
	ds_write2_b32 v14, v204, v205 offset1:1
	s_waitcnt vmcnt(12)
	ds_write2_b32 v63, v206, v207 offset1:1
	s_waitcnt vmcnt(11)
	ds_write2_b32 v72, v208, v209 offset1:1
	s_waitcnt vmcnt(10)
	ds_write2_b32 v73, v210, v211 offset1:1
	s_waitcnt vmcnt(9)
	ds_write2_b32 v74, v212, v213 offset1:1
	s_waitcnt vmcnt(8)
	ds_write2_b32 v75, v214, v215 offset1:1
	v_add_u32_e32 v63, s1, v4
	v_add_u32_e32 v14, 0xfcb20000, v63
	v_lshl_add_u64 v[200:201], v[14:15], 2, v[2:3]
	v_add_u32_e32 v14, 0xfcb21000, v63
	v_lshl_add_u64 v[202:203], v[14:15], 2, v[2:3]
	v_add_u32_e32 v14, 0xfcb22000, v63
	v_lshl_add_u64 v[204:205], v[14:15], 2, v[2:3]
	v_add_u32_e32 v14, 0xfcb23000, v63
	v_lshl_add_u64 v[206:207], v[14:15], 2, v[2:3]
	v_add_u32_e32 v14, 0xfcb24000, v63
	v_lshl_add_u64 v[208:209], v[14:15], 2, v[2:3]
	v_add_u32_e32 v14, 0xfcb25000, v63
	v_lshl_add_u64 v[210:211], v[14:15], 2, v[2:3]
	v_add_u32_e32 v14, 0xfcb26000, v63
	v_lshl_add_u64 v[212:213], v[14:15], 2, v[2:3]
	v_add_u32_e32 v14, 0xfcb27000, v63
	global_load_dwordx2 v[200:201], v[200:201], off
	s_nop 0
	global_load_dwordx2 v[202:203], v[202:203], off
	v_lshl_add_u64 v[214:215], v[14:15], 2, v[2:3]
	global_load_dwordx2 v[204:205], v[204:205], off
	s_nop 0
	global_load_dwordx2 v[206:207], v[206:207], off
	s_nop 0
	global_load_dwordx2 v[208:209], v[208:209], off
	s_nop 0
	global_load_dwordx2 v[210:211], v[210:211], off
	s_nop 0
	global_load_dwordx2 v[212:213], v[212:213], off
	s_nop 0
	global_load_dwordx2 v[214:215], v[214:215], off
	s_add_i32 s1, s1, 0x8000
	v_add_u32_e32 v14, 0x410, v5
	v_add_u32_e32 v63, 0x618, v5
	v_add_u32_e32 v72, 0x820, v5
	v_add_u32_e32 v73, 0xa28, v5
	v_add_u32_e32 v74, 0xc30, v5
	v_add_u32_e32 v75, 0xe38, v5
	s_waitcnt vmcnt(15)
	ds_write2_b32 v5, v6, v7 offset1:1
	s_waitcnt vmcnt(14)
	ds_write2_b32 v5, v8, v9 offset0:130 offset1:131
	v_add_u32_e32 v5, 0x1040, v5
	s_waitcnt vmcnt(13)
	ds_write2_b32 v14, v10, v11 offset1:1
	s_waitcnt vmcnt(12)
	ds_write2_b32 v63, v12, v13 offset1:1
	s_waitcnt vmcnt(11)
	ds_write2_b32 v72, v64, v65 offset1:1
	s_waitcnt vmcnt(10)
	ds_write2_b32 v73, v66, v67 offset1:1
	s_waitcnt vmcnt(9)
	ds_write2_b32 v74, v68, v69 offset1:1
	s_waitcnt vmcnt(8)
	ds_write2_b32 v75, v70, v71 offset1:1
	v_add_u32_e32 v14, 0x410, v5
	v_add_u32_e32 v63, 0x618, v5
	v_add_u32_e32 v72, 0x820, v5
	v_add_u32_e32 v73, 0xa28, v5
	v_add_u32_e32 v74, 0xc30, v5
	v_add_u32_e32 v75, 0xe38, v5
	s_waitcnt vmcnt(7)
	ds_write2_b32 v5, v200, v201 offset1:1
	s_waitcnt vmcnt(6)
	ds_write2_b32 v5, v202, v203 offset0:130 offset1:131
	v_add_u32_e32 v5, 0x1040, v5
	s_waitcnt vmcnt(5)
	ds_write2_b32 v14, v204, v205 offset1:1
	s_waitcnt vmcnt(4)
	ds_write2_b32 v63, v206, v207 offset1:1
	s_waitcnt vmcnt(3)
	ds_write2_b32 v72, v208, v209 offset1:1
	s_waitcnt vmcnt(2)
	ds_write2_b32 v73, v210, v211 offset1:1
	s_waitcnt vmcnt(1)
	ds_write2_b32 v74, v212, v213 offset1:1
	s_waitcnt vmcnt(0)
	ds_write2_b32 v75, v214, v215 offset1:1
	s_waitcnt lgkmcnt(0)
	ds_read2_b32 v[2:3], v81 offset1:65
	s_waitcnt lgkmcnt(0)
	v_cvt_pk_bf16_f32 v2, v2, v3
	ds_read2_b32 v[4:5], v81 offset0:130 offset1:195
	v_add_u32_e32 v12, 0x400, v81
	s_waitcnt lgkmcnt(0)
	v_cvt_pk_bf16_f32 v3, v4, v5
	ds_read2_b32 v[4:5], v12 offset0:4 offset1:69
	s_lshl_b32 s1, s96, 1
	s_waitcnt lgkmcnt(0)
	v_cvt_pk_bf16_f32 v4, v4, v5
	v_or_b32_e32 v5, s0, v80
	s_and_b32 s1, s1, 0x7fc0
	v_mul_u32_u24_e32 v8, 0x1600, v5
	s_add_i32 s8, s1, 0xffff9640
	v_lshlrev_b32_e32 v14, 1, v8
	v_lshl_add_u64 v[8:9], s[8:9], 1, v[22:23]
	v_lshl_add_u64 v[10:11], v[8:9], 0, v[14:15]
	ds_read2_b32 v[6:7], v12 offset0:134 offset1:199
	s_waitcnt lgkmcnt(0)
	v_cvt_pk_bf16_f32 v5, v6, v7
	global_store_dwordx4 v[10:11], v[2:5], off
	v_or_b32_e32 v10, s0, v82
	v_mul_u32_u24_e32 v10, 0x1600, v10
	ds_read2_b32 v[6:7], v81 offset0:8 offset1:73
	s_waitcnt lgkmcnt(0)
	v_cvt_pk_bf16_f32 v2, v6, v7
	ds_read2_b32 v[4:5], v81 offset0:138 offset1:203
	v_lshlrev_b32_e32 v14, 1, v10
	s_waitcnt lgkmcnt(0)
	v_cvt_pk_bf16_f32 v3, v4, v5
	ds_read2_b32 v[4:5], v12 offset0:12 offset1:77
	v_lshl_add_u64 v[10:11], v[8:9], 0, v[14:15]
	s_waitcnt lgkmcnt(0)
	v_cvt_pk_bf16_f32 v4, v4, v5
	ds_read2_b32 v[6:7], v12 offset0:142 offset1:207
	s_waitcnt lgkmcnt(0)
	v_cvt_pk_bf16_f32 v5, v6, v7
	global_store_dwordx4 v[10:11], v[2:5], off
	v_or_b32_e32 v10, s0, v83
	v_mul_u32_u24_e32 v10, 0x1600, v10
	ds_read2_b32 v[6:7], v81 offset0:16 offset1:81
	s_waitcnt lgkmcnt(0)
	v_cvt_pk_bf16_f32 v2, v6, v7
	ds_read2_b32 v[4:5], v81 offset0:146 offset1:211
	v_lshlrev_b32_e32 v14, 1, v10
	s_waitcnt lgkmcnt(0)
	v_cvt_pk_bf16_f32 v3, v4, v5
	ds_read2_b32 v[4:5], v12 offset0:20 offset1:85
	v_lshl_add_u64 v[10:11], v[8:9], 0, v[14:15]
	s_waitcnt lgkmcnt(0)
	v_cvt_pk_bf16_f32 v4, v4, v5
	ds_read2_b32 v[6:7], v12 offset0:150 offset1:215
	s_waitcnt lgkmcnt(0)
	v_cvt_pk_bf16_f32 v5, v6, v7
	global_store_dwordx4 v[10:11], v[2:5], off
	v_or_b32_e32 v10, s0, v84
	v_mul_u32_u24_e32 v10, 0x1600, v10
	ds_read2_b32 v[6:7], v81 offset0:24 offset1:89
	s_waitcnt lgkmcnt(0)
	v_cvt_pk_bf16_f32 v2, v6, v7
	ds_read2_b32 v[4:5], v81 offset0:154 offset1:219
	v_lshlrev_b32_e32 v14, 1, v10
	s_waitcnt lgkmcnt(0)
	v_cvt_pk_bf16_f32 v3, v4, v5
	ds_read2_b32 v[4:5], v12 offset0:28 offset1:93
	v_lshl_add_u64 v[10:11], v[8:9], 0, v[14:15]
	s_waitcnt lgkmcnt(0)
	v_cvt_pk_bf16_f32 v4, v4, v5
	ds_read2_b32 v[6:7], v12 offset0:158 offset1:223
	s_waitcnt lgkmcnt(0)
	v_cvt_pk_bf16_f32 v5, v6, v7
	global_store_dwordx4 v[10:11], v[2:5], off
	v_or_b32_e32 v10, s0, v85
	v_mul_u32_u24_e32 v10, 0x1600, v10
	ds_read2_b32 v[6:7], v81 offset0:32 offset1:97
	s_waitcnt lgkmcnt(0)
	v_cvt_pk_bf16_f32 v2, v6, v7
	ds_read2_b32 v[4:5], v81 offset0:162 offset1:227
	v_lshlrev_b32_e32 v14, 1, v10
	s_waitcnt lgkmcnt(0)
	v_cvt_pk_bf16_f32 v3, v4, v5
	ds_read2_b32 v[4:5], v12 offset0:36 offset1:101
	v_lshl_add_u64 v[10:11], v[8:9], 0, v[14:15]
	s_waitcnt lgkmcnt(0)
	v_cvt_pk_bf16_f32 v4, v4, v5
	ds_read2_b32 v[6:7], v12 offset0:166 offset1:231
	s_waitcnt lgkmcnt(0)
	v_cvt_pk_bf16_f32 v5, v6, v7
	global_store_dwordx4 v[10:11], v[2:5], off
	v_or_b32_e32 v10, s0, v86
	v_mul_u32_u24_e32 v10, 0x1600, v10
	ds_read2_b32 v[6:7], v81 offset0:40 offset1:105
	s_waitcnt lgkmcnt(0)
	v_cvt_pk_bf16_f32 v2, v6, v7
	ds_read2_b32 v[4:5], v81 offset0:170 offset1:235
	v_lshlrev_b32_e32 v14, 1, v10
	s_waitcnt lgkmcnt(0)
	v_cvt_pk_bf16_f32 v3, v4, v5
	ds_read2_b32 v[4:5], v12 offset0:44 offset1:109
	v_lshl_add_u64 v[10:11], v[8:9], 0, v[14:15]
	s_waitcnt lgkmcnt(0)
	v_cvt_pk_bf16_f32 v4, v4, v5
	ds_read2_b32 v[6:7], v12 offset0:174 offset1:239
	s_waitcnt lgkmcnt(0)
	v_cvt_pk_bf16_f32 v5, v6, v7
	global_store_dwordx4 v[10:11], v[2:5], off
	v_or_b32_e32 v10, s0, v87
	ds_read2_b32 v[6:7], v81 offset0:48 offset1:113
	s_waitcnt lgkmcnt(0)
	v_cvt_pk_bf16_f32 v2, v6, v7
	ds_read2_b32 v[4:5], v81 offset0:178 offset1:243
	v_mul_u32_u24_e32 v10, 0x1600, v10
	s_waitcnt lgkmcnt(0)
	v_cvt_pk_bf16_f32 v3, v4, v5
	ds_read2_b32 v[4:5], v12 offset0:52 offset1:117
	v_lshlrev_b32_e32 v14, 1, v10
	s_waitcnt lgkmcnt(0)
	v_cvt_pk_bf16_f32 v4, v4, v5
	ds_read2_b32 v[6:7], v12 offset0:182 offset1:247
	s_waitcnt lgkmcnt(0)
	v_cvt_pk_bf16_f32 v5, v6, v7
	v_lshl_add_u64 v[10:11], v[8:9], 0, v[14:15]
	ds_read2_b32 v[6:7], v81 offset0:56 offset1:121
	global_store_dwordx4 v[10:11], v[2:5], off
	s_waitcnt lgkmcnt(0)
	s_nop 0
	v_cvt_pk_bf16_f32 v2, v6, v7
	ds_read2_b32 v[4:5], v81 offset0:186 offset1:251
	s_waitcnt lgkmcnt(0)
	v_cvt_pk_bf16_f32 v3, v4, v5
	ds_read2_b32 v[4:5], v12 offset0:60 offset1:125
	s_waitcnt lgkmcnt(0)
	v_cvt_pk_bf16_f32 v4, v4, v5
	v_or_b32_e32 v5, s0, v88
	v_mul_u32_u24_e32 v5, 0x1600, v5
	ds_read2_b32 v[6:7], v12 offset0:190 offset1:255
	v_lshlrev_b32_e32 v14, 1, v5
	s_waitcnt lgkmcnt(0)
	v_cvt_pk_bf16_f32 v5, v6, v7
	v_lshl_add_u64 v[6:7], v[8:9], 0, v[14:15]
	global_store_dwordx4 v[6:7], v[2:5], off
	s_waitcnt lgkmcnt(0)

.LBB0_40:
	v_lshl_add_u64 v[66:67], v[10:11], 0, s[0:1]
	v_add_co_u32_e32 v76, vcc, 0xb000, v66
	v_lshl_add_u64 v[64:65], v[12:13], 0, s[0:1]
	s_nop 0
	v_addc_co_u32_e32 v77, vcc, 0, v67, vcc
	v_add_co_u32_e32 v108, vcc, 0x16000, v66
	v_lshl_add_u64 v[68:69], v[8:9], 0, s[0:1]
	s_nop 0
	v_addc_co_u32_e32 v109, vcc, 0, v67, vcc
	v_lshl_add_u64 v[70:71], v[6:7], 0, s[0:1]
	v_lshl_add_u64 v[72:73], v[4:5], 0, s[0:1]
	v_lshl_add_u64 v[74:75], v[2:3], 0, s[0:1]
	v_add_co_u32_e32 v66, vcc, 0x21000, v66
	global_load_dwordx2 v[64:65], v[64:65], off
	s_nop 0
	global_load_dwordx2 v[68:69], v[68:69], off
	s_nop 0
	global_load_dwordx2 v[70:71], v[70:71], off
	s_nop 0
	global_load_dwordx2 v[72:73], v[72:73], off
	s_nop 0
	global_load_dwordx2 v[74:75], v[74:75], off
	v_addc_co_u32_e32 v67, vcc, 0, v67, vcc
	global_load_dwordx2 v[76:77], v[76:77], off
	s_nop 0
	global_load_dwordx2 v[108:109], v[108:109], off
	s_nop 0
	global_load_dwordx2 v[66:67], v[66:67], off
	s_add_u32 s0, s0, 0x58000
	s_addc_u32 s1, s1, 0
	v_lshl_add_u64 v[214:215], v[10:11], 0, s[0:1]
	v_add_co_u32_e32 v210, vcc, 0xb000, v214
	v_lshl_add_u64 v[200:201], v[12:13], 0, s[0:1]
	s_nop 0
	v_addc_co_u32_e32 v211, vcc, 0, v215, vcc
	v_add_co_u32_e32 v212, vcc, 0x16000, v214
	v_lshl_add_u64 v[202:203], v[8:9], 0, s[0:1]
	s_nop 0
	v_addc_co_u32_e32 v213, vcc, 0, v215, vcc
	v_lshl_add_u64 v[204:205], v[6:7], 0, s[0:1]
	v_lshl_add_u64 v[206:207], v[4:5], 0, s[0:1]
	v_lshl_add_u64 v[208:209], v[2:3], 0, s[0:1]
	v_add_co_u32_e32 v214, vcc, 0x21000, v214
	global_load_dwordx2 v[200:201], v[200:201], off
	s_nop 0
	global_load_dwordx2 v[202:203], v[202:203], off
	s_nop 0
	global_load_dwordx2 v[204:205], v[204:205], off
	s_nop 0
	global_load_dwordx2 v[206:207], v[206:207], off
	s_nop 0
	global_load_dwordx2 v[208:209], v[208:209], off
	v_addc_co_u32_e32 v215, vcc, 0, v215, vcc
	global_load_dwordx2 v[210:211], v[210:211], off
	s_nop 0
	global_load_dwordx2 v[212:213], v[212:213], off
	s_nop 0
	global_load_dwordx2 v[214:215], v[214:215], off
	s_add_u32 s0, s0, 0x58000
	s_addc_u32 s1, s1, 0
	v_add_u32_e32 v63, 0x410, v14
	v_add_u32_e32 v110, 0x618, v14
	v_add_u32_e32 v111, 0x820, v14
	v_add_u32_e32 v112, 0xa28, v14
	v_add_u32_e32 v113, 0xc30, v14
	v_add_u32_e32 v114, 0xe38, v14
	s_waitcnt vmcnt(15)
	ds_write2_b32 v14, v64, v65 offset1:1
	s_waitcnt vmcnt(14)
	ds_write2_b32 v111, v68, v69 offset1:1
	s_waitcnt vmcnt(13)
	ds_write2_b32 v112, v70, v71 offset1:1
	s_waitcnt vmcnt(12)
	ds_write2_b32 v113, v72, v73 offset1:1
	s_waitcnt vmcnt(11)
	ds_write2_b32 v114, v74, v75 offset1:1
	s_waitcnt vmcnt(10)
	ds_write2_b32 v14, v76, v77 offset0:130 offset1:131
	v_add_u32_e32 v14, 0x1040, v14
	s_waitcnt vmcnt(9)
	ds_write2_b32 v63, v108, v109 offset1:1
	s_waitcnt vmcnt(8)
	ds_write2_b32 v110, v66, v67 offset1:1
	v_lshl_add_u64 v[66:67], v[10:11], 0, s[0:1]
	v_add_co_u32_e32 v76, vcc, 0xb000, v66
	v_lshl_add_u64 v[64:65], v[12:13], 0, s[0:1]
	s_nop 0
	v_addc_co_u32_e32 v77, vcc, 0, v67, vcc
	v_add_co_u32_e32 v108, vcc, 0x16000, v66
	v_lshl_add_u64 v[68:69], v[8:9], 0, s[0:1]
	s_nop 0
	v_addc_co_u32_e32 v109, vcc, 0, v67, vcc
	v_lshl_add_u64 v[70:71], v[6:7], 0, s[0:1]
	v_lshl_add_u64 v[72:73], v[4:5], 0, s[0:1]
	v_lshl_add_u64 v[74:75], v[2:3], 0, s[0:1]
	v_add_co_u32_e32 v66, vcc, 0x21000, v66
	global_load_dwordx2 v[64:65], v[64:65], off
	s_nop 0
	global_load_dwordx2 v[68:69], v[68:69], off
	s_nop 0
	global_load_dwordx2 v[70:71], v[70:71], off
	s_nop 0
	global_load_dwordx2 v[72:73], v[72:73], off
	s_nop 0
	global_load_dwordx2 v[74:75], v[74:75], off
	v_addc_co_u32_e32 v67, vcc, 0, v67, vcc
	global_load_dwordx2 v[76:77], v[76:77], off
	s_nop 0
	global_load_dwordx2 v[108:109], v[108:109], off
	s_nop 0
	global_load_dwordx2 v[66:67], v[66:67], off
	s_add_u32 s0, s0, 0x58000
	s_addc_u32 s1, s1, 0
	v_add_u32_e32 v63, 0x410, v14
	v_add_u32_e32 v110, 0x618, v14
	v_add_u32_e32 v111, 0x820, v14
	v_add_u32_e32 v112, 0xa28, v14
	v_add_u32_e32 v113, 0xc30, v14
	v_add_u32_e32 v114, 0xe38, v14
	s_waitcnt vmcnt(15)
	ds_write2_b32 v14, v200, v201 offset1:1
	s_waitcnt vmcnt(14)
	ds_write2_b32 v111, v202, v203 offset1:1
	s_waitcnt vmcnt(13)
	ds_write2_b32 v112, v204, v205 offset1:1
	s_waitcnt vmcnt(12)
	ds_write2_b32 v113, v206, v207 offset1:1
	s_waitcnt vmcnt(11)
	ds_write2_b32 v114, v208, v209 offset1:1
	s_waitcnt vmcnt(10)
	ds_write2_b32 v14, v210, v211 offset0:130 offset1:131
	v_add_u32_e32 v14, 0x1040, v14
	s_waitcnt vmcnt(9)
	ds_write2_b32 v63, v212, v213 offset1:1
	s_waitcnt vmcnt(8)
	ds_write2_b32 v110, v214, v215 offset1:1
	v_lshl_add_u64 v[214:215], v[10:11], 0, s[0:1]
	v_add_co_u32_e32 v210, vcc, 0xb000, v214
	v_lshl_add_u64 v[200:201], v[12:13], 0, s[0:1]
	s_nop 0
	v_addc_co_u32_e32 v211, vcc, 0, v215, vcc
	v_add_co_u32_e32 v212, vcc, 0x16000, v214
	v_lshl_add_u64 v[202:203], v[8:9], 0, s[0:1]
	s_nop 0
	v_addc_co_u32_e32 v213, vcc, 0, v215, vcc
	v_lshl_add_u64 v[204:205], v[6:7], 0, s[0:1]
	v_lshl_add_u64 v[206:207], v[4:5], 0, s[0:1]
	v_lshl_add_u64 v[208:209], v[2:3], 0, s[0:1]
	v_add_co_u32_e32 v214, vcc, 0x21000, v214
	global_load_dwordx2 v[200:201], v[200:201], off
	s_nop 0
	global_load_dwordx2 v[202:203], v[202:203], off
	s_nop 0
	global_load_dwordx2 v[204:205], v[204:205], off
	s_nop 0
	global_load_dwordx2 v[206:207], v[206:207], off
	s_nop 0
	global_load_dwordx2 v[208:209], v[208:209], off
	v_addc_co_u32_e32 v215, vcc, 0, v215, vcc
	global_load_dwordx2 v[210:211], v[210:211], off
	s_nop 0
	global_load_dwordx2 v[212:213], v[212:213], off
	s_nop 0
	global_load_dwordx2 v[214:215], v[214:215], off
	s_add_u32 s0, s0, 0x58000
	s_addc_u32 s1, s1, 0
	v_add_u32_e32 v63, 0x410, v14
	v_add_u32_e32 v110, 0x618, v14
	v_add_u32_e32 v111, 0x820, v14
	v_add_u32_e32 v112, 0xa28, v14
	v_add_u32_e32 v113, 0xc30, v14
	v_add_u32_e32 v114, 0xe38, v14
	s_waitcnt vmcnt(15)
	ds_write2_b32 v14, v64, v65 offset1:1
	s_waitcnt vmcnt(14)
	ds_write2_b32 v111, v68, v69 offset1:1
	s_waitcnt vmcnt(13)
	ds_write2_b32 v112, v70, v71 offset1:1
	s_waitcnt vmcnt(12)
	ds_write2_b32 v113, v72, v73 offset1:1
	s_waitcnt vmcnt(11)
	ds_write2_b32 v114, v74, v75 offset1:1
	s_waitcnt vmcnt(10)
	ds_write2_b32 v14, v76, v77 offset0:130 offset1:131
	v_add_u32_e32 v14, 0x1040, v14
	s_waitcnt vmcnt(9)
	ds_write2_b32 v63, v108, v109 offset1:1
	s_waitcnt vmcnt(8)
	ds_write2_b32 v110, v66, v67 offset1:1
	v_add_u32_e32 v63, 0x410, v14
	v_add_u32_e32 v110, 0x618, v14
	v_add_u32_e32 v111, 0x820, v14
	v_add_u32_e32 v112, 0xa28, v14
	v_add_u32_e32 v113, 0xc30, v14
	v_add_u32_e32 v114, 0xe38, v14
	s_waitcnt vmcnt(7)
	ds_write2_b32 v14, v200, v201 offset1:1
	s_waitcnt vmcnt(6)
	ds_write2_b32 v111, v202, v203 offset1:1
	s_waitcnt vmcnt(5)
	ds_write2_b32 v112, v204, v205 offset1:1
	s_waitcnt vmcnt(4)
	ds_write2_b32 v113, v206, v207 offset1:1
	s_waitcnt vmcnt(3)
	ds_write2_b32 v114, v208, v209 offset1:1
	s_waitcnt vmcnt(2)
	ds_write2_b32 v14, v210, v211 offset0:130 offset1:131
	v_add_u32_e32 v14, 0x1040, v14
	s_waitcnt vmcnt(1)
	ds_write2_b32 v63, v212, v213 offset1:1
	s_waitcnt vmcnt(0)
	ds_write2_b32 v110, v214, v215 offset1:1
	s_lshl_b32 s0, s2, 7
	s_and_b32 s1, s3, 64
	s_waitcnt lgkmcnt(0)
	s_or_b32 s0, s1, s0
	ds_read2_b32 v[2:3], v81 offset1:65
	s_and_b32 s2, 0xffff, s4
	s_bitset1_b32 s0, 7
	s_waitcnt lgkmcnt(0)
	v_cvt_pk_bf16_f32 v2, v2, v3
	ds_read2_b32 v[4:5], v81 offset0:130 offset1:195
	v_add_u32_e32 v12, 0x400, v81
	s_lshl_b32 s8, s2, 1
	v_or_b32_e32 v10, s0, v80
	s_waitcnt lgkmcnt(0)
	v_cvt_pk_bf16_f32 v3, v4, v5
	ds_read2_b32 v[4:5], v12 offset0:4 offset1:69
	v_lshl_add_u64 v[8:9], v[24:25], 0, s[8:9]
	v_lshlrev_b32_e32 v14, 12, v10
	s_waitcnt lgkmcnt(0)
	v_cvt_pk_bf16_f32 v4, v4, v5
	ds_read2_b32 v[6:7], v12 offset0:134 offset1:199
	s_waitcnt lgkmcnt(0)
	v_cvt_pk_bf16_f32 v5, v6, v7
	v_lshl_add_u64 v[10:11], v[8:9], 0, v[14:15]
	ds_read2_b32 v[6:7], v81 offset0:8 offset1:73
	global_store_dwordx4 v[10:11], v[2:5], off
	v_or_b32_e32 v10, s0, v82
	v_lshlrev_b32_e32 v14, 12, v10
	s_waitcnt lgkmcnt(0)
	v_cvt_pk_bf16_f32 v2, v6, v7
	ds_read2_b32 v[4:5], v81 offset0:138 offset1:203
	s_waitcnt lgkmcnt(0)
	v_cvt_pk_bf16_f32 v3, v4, v5
	ds_read2_b32 v[4:5], v12 offset0:12 offset1:77
	s_waitcnt lgkmcnt(0)
	v_cvt_pk_bf16_f32 v4, v4, v5
	ds_read2_b32 v[6:7], v12 offset0:142 offset1:207
	s_waitcnt lgkmcnt(0)
	v_cvt_pk_bf16_f32 v5, v6, v7
	v_lshl_add_u64 v[10:11], v[8:9], 0, v[14:15]
	ds_read2_b32 v[6:7], v81 offset0:16 offset1:81
	global_store_dwordx4 v[10:11], v[2:5], off
	v_or_b32_e32 v10, s0, v83
	v_lshlrev_b32_e32 v14, 12, v10
	s_waitcnt lgkmcnt(0)
	v_cvt_pk_bf16_f32 v2, v6, v7
	ds_read2_b32 v[4:5], v81 offset0:146 offset1:211
	s_waitcnt lgkmcnt(0)
	v_cvt_pk_bf16_f32 v3, v4, v5
	ds_read2_b32 v[4:5], v12 offset0:20 offset1:85
	s_waitcnt lgkmcnt(0)
	v_cvt_pk_bf16_f32 v4, v4, v5
	ds_read2_b32 v[6:7], v12 offset0:150 offset1:215
	s_waitcnt lgkmcnt(0)
	v_cvt_pk_bf16_f32 v5, v6, v7
	v_lshl_add_u64 v[10:11], v[8:9], 0, v[14:15]
	ds_read2_b32 v[6:7], v81 offset0:24 offset1:89
	global_store_dwordx4 v[10:11], v[2:5], off
	v_or_b32_e32 v10, s0, v84
	v_lshlrev_b32_e32 v14, 12, v10
	s_waitcnt lgkmcnt(0)
	v_cvt_pk_bf16_f32 v2, v6, v7
	ds_read2_b32 v[4:5], v81 offset0:154 offset1:219
	s_waitcnt lgkmcnt(0)
	v_cvt_pk_bf16_f32 v3, v4, v5
	ds_read2_b32 v[4:5], v12 offset0:28 offset1:93
	s_waitcnt lgkmcnt(0)
	v_cvt_pk_bf16_f32 v4, v4, v5
	ds_read2_b32 v[6:7], v12 offset0:158 offset1:223
	s_waitcnt lgkmcnt(0)
	v_cvt_pk_bf16_f32 v5, v6, v7
	v_lshl_add_u64 v[10:11], v[8:9], 0, v[14:15]
	ds_read2_b32 v[6:7], v81 offset0:32 offset1:97
	global_store_dwordx4 v[10:11], v[2:5], off
	v_or_b32_e32 v10, s0, v85
	v_lshlrev_b32_e32 v14, 12, v10
	s_waitcnt lgkmcnt(0)
	v_cvt_pk_bf16_f32 v2, v6, v7
	ds_read2_b32 v[4:5], v81 offset0:162 offset1:227
	s_waitcnt lgkmcnt(0)
	v_cvt_pk_bf16_f32 v3, v4, v5
	ds_read2_b32 v[4:5], v12 offset0:36 offset1:101
	s_waitcnt lgkmcnt(0)
	v_cvt_pk_bf16_f32 v4, v4, v5
	ds_read2_b32 v[6:7], v12 offset0:166 offset1:231
	s_waitcnt lgkmcnt(0)
	v_cvt_pk_bf16_f32 v5, v6, v7
	v_lshl_add_u64 v[10:11], v[8:9], 0, v[14:15]
	ds_read2_b32 v[6:7], v81 offset0:40 offset1:105
	global_store_dwordx4 v[10:11], v[2:5], off
	v_or_b32_e32 v10, s0, v86
	v_lshlrev_b32_e32 v14, 12, v10
	s_waitcnt lgkmcnt(0)
	v_cvt_pk_bf16_f32 v2, v6, v7
	ds_read2_b32 v[4:5], v81 offset0:170 offset1:235
	s_waitcnt lgkmcnt(0)
	v_cvt_pk_bf16_f32 v3, v4, v5
	ds_read2_b32 v[4:5], v12 offset0:44 offset1:109
	s_waitcnt lgkmcnt(0)
	v_cvt_pk_bf16_f32 v4, v4, v5
	ds_read2_b32 v[6:7], v12 offset0:174 offset1:239
	s_waitcnt lgkmcnt(0)
	v_cvt_pk_bf16_f32 v5, v6, v7
	v_lshl_add_u64 v[10:11], v[8:9], 0, v[14:15]
	ds_read2_b32 v[6:7], v81 offset0:48 offset1:113
	global_store_dwordx4 v[10:11], v[2:5], off
	v_or_b32_e32 v10, s0, v87
	v_lshlrev_b32_e32 v14, 12, v10
	s_waitcnt lgkmcnt(0)
	v_cvt_pk_bf16_f32 v2, v6, v7
	ds_read2_b32 v[4:5], v81 offset0:178 offset1:243
	s_waitcnt lgkmcnt(0)
	v_cvt_pk_bf16_f32 v3, v4, v5
	ds_read2_b32 v[4:5], v12 offset0:52 offset1:117
	s_waitcnt lgkmcnt(0)
	v_cvt_pk_bf16_f32 v4, v4, v5
	ds_read2_b32 v[6:7], v12 offset0:182 offset1:247
	s_waitcnt lgkmcnt(0)
	v_cvt_pk_bf16_f32 v5, v6, v7
	v_lshl_add_u64 v[10:11], v[8:9], 0, v[14:15]
	ds_read2_b32 v[6:7], v81 offset0:56 offset1:121
	global_store_dwordx4 v[10:11], v[2:5], off
	s_waitcnt lgkmcnt(0)
	s_nop 0
	v_cvt_pk_bf16_f32 v2, v6, v7
	ds_read2_b32 v[4:5], v81 offset0:186 offset1:251
	s_waitcnt lgkmcnt(0)
	v_cvt_pk_bf16_f32 v3, v4, v5
	ds_read2_b32 v[4:5], v12 offset0:60 offset1:125
	s_waitcnt lgkmcnt(0)
	v_cvt_pk_bf16_f32 v4, v4, v5
	v_or_b32_e32 v5, s0, v88
	ds_read2_b32 v[6:7], v12 offset0:190 offset1:255
	v_lshlrev_b32_e32 v14, 12, v5
	s_waitcnt lgkmcnt(0)
	v_cvt_pk_bf16_f32 v5, v6, v7
	v_lshl_add_u64 v[6:7], v[8:9], 0, v[14:15]
	global_store_dwordx4 v[6:7], v[2:5], off
	s_waitcnt lgkmcnt(0)

.LBB0_45:
	v_lshl_add_u64 v[66:67], v[10:11], 0, s[0:1]
	v_add_co_u32_e32 v76, vcc, 0xb000, v66
	v_lshl_add_u64 v[64:65], v[12:13], 0, s[0:1]
	s_nop 0
	v_addc_co_u32_e32 v77, vcc, 0, v67, vcc
	v_add_co_u32_e32 v108, vcc, 0x16000, v66
	v_lshl_add_u64 v[68:69], v[8:9], 0, s[0:1]
	s_nop 0
	v_addc_co_u32_e32 v109, vcc, 0, v67, vcc
	v_lshl_add_u64 v[70:71], v[6:7], 0, s[0:1]
	v_lshl_add_u64 v[72:73], v[4:5], 0, s[0:1]
	v_lshl_add_u64 v[74:75], v[2:3], 0, s[0:1]
	v_add_co_u32_e32 v66, vcc, 0x21000, v66
	global_load_dwordx2 v[64:65], v[64:65], off
	s_nop 0
	global_load_dwordx2 v[68:69], v[68:69], off
	s_nop 0
	global_load_dwordx2 v[70:71], v[70:71], off
	s_nop 0
	global_load_dwordx2 v[72:73], v[72:73], off
	s_nop 0
	global_load_dwordx2 v[74:75], v[74:75], off
	v_addc_co_u32_e32 v67, vcc, 0, v67, vcc
	global_load_dwordx2 v[76:77], v[76:77], off
	s_nop 0
	global_load_dwordx2 v[108:109], v[108:109], off
	s_nop 0
	global_load_dwordx2 v[66:67], v[66:67], off
	s_add_u32 s0, s0, 0x58000
	s_addc_u32 s1, s1, 0
	v_lshl_add_u64 v[214:215], v[10:11], 0, s[0:1]
	v_add_co_u32_e32 v210, vcc, 0xb000, v214
	v_lshl_add_u64 v[200:201], v[12:13], 0, s[0:1]
	s_nop 0
	v_addc_co_u32_e32 v211, vcc, 0, v215, vcc
	v_add_co_u32_e32 v212, vcc, 0x16000, v214
	v_lshl_add_u64 v[202:203], v[8:9], 0, s[0:1]
	s_nop 0
	v_addc_co_u32_e32 v213, vcc, 0, v215, vcc
	v_lshl_add_u64 v[204:205], v[6:7], 0, s[0:1]
	v_lshl_add_u64 v[206:207], v[4:5], 0, s[0:1]
	v_lshl_add_u64 v[208:209], v[2:3], 0, s[0:1]
	v_add_co_u32_e32 v214, vcc, 0x21000, v214
	global_load_dwordx2 v[200:201], v[200:201], off
	s_nop 0
	global_load_dwordx2 v[202:203], v[202:203], off
	s_nop 0
	global_load_dwordx2 v[204:205], v[204:205], off
	s_nop 0
	global_load_dwordx2 v[206:207], v[206:207], off
	s_nop 0
	global_load_dwordx2 v[208:209], v[208:209], off
	v_addc_co_u32_e32 v215, vcc, 0, v215, vcc
	global_load_dwordx2 v[210:211], v[210:211], off
	s_nop 0
	global_load_dwordx2 v[212:213], v[212:213], off
	s_nop 0
	global_load_dwordx2 v[214:215], v[214:215], off
	s_add_u32 s0, s0, 0x58000
	s_addc_u32 s1, s1, 0
	v_add_u32_e32 v63, 0x410, v14
	v_add_u32_e32 v110, 0x618, v14
	v_add_u32_e32 v111, 0x820, v14
	v_add_u32_e32 v112, 0xa28, v14
	v_add_u32_e32 v113, 0xc30, v14
	v_add_u32_e32 v114, 0xe38, v14
	s_waitcnt vmcnt(15)
	ds_write2_b32 v14, v64, v65 offset1:1
	s_waitcnt vmcnt(14)
	ds_write2_b32 v111, v68, v69 offset1:1
	s_waitcnt vmcnt(13)
	ds_write2_b32 v112, v70, v71 offset1:1
	s_waitcnt vmcnt(12)
	ds_write2_b32 v113, v72, v73 offset1:1
	s_waitcnt vmcnt(11)
	ds_write2_b32 v114, v74, v75 offset1:1
	s_waitcnt vmcnt(10)
	ds_write2_b32 v14, v76, v77 offset0:130 offset1:131
	v_add_u32_e32 v14, 0x1040, v14
	s_waitcnt vmcnt(9)
	ds_write2_b32 v63, v108, v109 offset1:1
	s_waitcnt vmcnt(8)
	ds_write2_b32 v110, v66, v67 offset1:1
	v_lshl_add_u64 v[66:67], v[10:11], 0, s[0:1]
	v_add_co_u32_e32 v76, vcc, 0xb000, v66
	v_lshl_add_u64 v[64:65], v[12:13], 0, s[0:1]
	s_nop 0
	v_addc_co_u32_e32 v77, vcc, 0, v67, vcc
	v_add_co_u32_e32 v108, vcc, 0x16000, v66
	v_lshl_add_u64 v[68:69], v[8:9], 0, s[0:1]
	s_nop 0
	v_addc_co_u32_e32 v109, vcc, 0, v67, vcc
	v_lshl_add_u64 v[70:71], v[6:7], 0, s[0:1]
	v_lshl_add_u64 v[72:73], v[4:5], 0, s[0:1]
	v_lshl_add_u64 v[74:75], v[2:3], 0, s[0:1]
	v_add_co_u32_e32 v66, vcc, 0x21000, v66
	global_load_dwordx2 v[64:65], v[64:65], off
	s_nop 0
	global_load_dwordx2 v[68:69], v[68:69], off
	s_nop 0
	global_load_dwordx2 v[70:71], v[70:71], off
	s_nop 0
	global_load_dwordx2 v[72:73], v[72:73], off
	s_nop 0
	global_load_dwordx2 v[74:75], v[74:75], off
	v_addc_co_u32_e32 v67, vcc, 0, v67, vcc
	global_load_dwordx2 v[76:77], v[76:77], off
	s_nop 0
	global_load_dwordx2 v[108:109], v[108:109], off
	s_nop 0
	global_load_dwordx2 v[66:67], v[66:67], off
	s_add_u32 s0, s0, 0x58000
	s_addc_u32 s1, s1, 0
	v_add_u32_e32 v63, 0x410, v14
	v_add_u32_e32 v110, 0x618, v14
	v_add_u32_e32 v111, 0x820, v14
	v_add_u32_e32 v112, 0xa28, v14
	v_add_u32_e32 v113, 0xc30, v14
	v_add_u32_e32 v114, 0xe38, v14
	s_waitcnt vmcnt(15)
	ds_write2_b32 v14, v200, v201 offset1:1
	s_waitcnt vmcnt(14)
	ds_write2_b32 v111, v202, v203 offset1:1
	s_waitcnt vmcnt(13)
	ds_write2_b32 v112, v204, v205 offset1:1
	s_waitcnt vmcnt(12)
	ds_write2_b32 v113, v206, v207 offset1:1
	s_waitcnt vmcnt(11)
	ds_write2_b32 v114, v208, v209 offset1:1
	s_waitcnt vmcnt(10)
	ds_write2_b32 v14, v210, v211 offset0:130 offset1:131
	v_add_u32_e32 v14, 0x1040, v14
	s_waitcnt vmcnt(9)
	ds_write2_b32 v63, v212, v213 offset1:1
	s_waitcnt vmcnt(8)
	ds_write2_b32 v110, v214, v215 offset1:1
	v_lshl_add_u64 v[214:215], v[10:11], 0, s[0:1]
	v_add_co_u32_e32 v210, vcc, 0xb000, v214
	v_lshl_add_u64 v[200:201], v[12:13], 0, s[0:1]
	s_nop 0
	v_addc_co_u32_e32 v211, vcc, 0, v215, vcc
	v_add_co_u32_e32 v212, vcc, 0x16000, v214
	v_lshl_add_u64 v[202:203], v[8:9], 0, s[0:1]
	s_nop 0
	v_addc_co_u32_e32 v213, vcc, 0, v215, vcc
	v_lshl_add_u64 v[204:205], v[6:7], 0, s[0:1]
	v_lshl_add_u64 v[206:207], v[4:5], 0, s[0:1]
	v_lshl_add_u64 v[208:209], v[2:3], 0, s[0:1]
	v_add_co_u32_e32 v214, vcc, 0x21000, v214
	global_load_dwordx2 v[200:201], v[200:201], off
	s_nop 0
	global_load_dwordx2 v[202:203], v[202:203], off
	s_nop 0
	global_load_dwordx2 v[204:205], v[204:205], off
	s_nop 0
	global_load_dwordx2 v[206:207], v[206:207], off
	s_nop 0
	global_load_dwordx2 v[208:209], v[208:209], off
	v_addc_co_u32_e32 v215, vcc, 0, v215, vcc
	global_load_dwordx2 v[210:211], v[210:211], off
	s_nop 0
	global_load_dwordx2 v[212:213], v[212:213], off
	s_nop 0
	global_load_dwordx2 v[214:215], v[214:215], off
	s_add_u32 s0, s0, 0x58000
	s_addc_u32 s1, s1, 0
	v_add_u32_e32 v63, 0x410, v14
	v_add_u32_e32 v110, 0x618, v14
	v_add_u32_e32 v111, 0x820, v14
	v_add_u32_e32 v112, 0xa28, v14
	v_add_u32_e32 v113, 0xc30, v14
	v_add_u32_e32 v114, 0xe38, v14
	s_waitcnt vmcnt(15)
	ds_write2_b32 v14, v64, v65 offset1:1
	s_waitcnt vmcnt(14)
	ds_write2_b32 v111, v68, v69 offset1:1
	s_waitcnt vmcnt(13)
	ds_write2_b32 v112, v70, v71 offset1:1
	s_waitcnt vmcnt(12)
	ds_write2_b32 v113, v72, v73 offset1:1
	s_waitcnt vmcnt(11)
	ds_write2_b32 v114, v74, v75 offset1:1
	s_waitcnt vmcnt(10)
	ds_write2_b32 v14, v76, v77 offset0:130 offset1:131
	v_add_u32_e32 v14, 0x1040, v14
	s_waitcnt vmcnt(9)
	ds_write2_b32 v63, v108, v109 offset1:1
	s_waitcnt vmcnt(8)
	ds_write2_b32 v110, v66, v67 offset1:1
	v_add_u32_e32 v63, 0x410, v14
	v_add_u32_e32 v110, 0x618, v14
	v_add_u32_e32 v111, 0x820, v14
	v_add_u32_e32 v112, 0xa28, v14
	v_add_u32_e32 v113, 0xc30, v14
	v_add_u32_e32 v114, 0xe38, v14
	s_waitcnt vmcnt(7)
	ds_write2_b32 v14, v200, v201 offset1:1
	s_waitcnt vmcnt(6)
	ds_write2_b32 v111, v202, v203 offset1:1
	s_waitcnt vmcnt(5)
	ds_write2_b32 v112, v204, v205 offset1:1
	s_waitcnt vmcnt(4)
	ds_write2_b32 v113, v206, v207 offset1:1
	s_waitcnt vmcnt(3)
	ds_write2_b32 v114, v208, v209 offset1:1
	s_waitcnt vmcnt(2)
	ds_write2_b32 v14, v210, v211 offset0:130 offset1:131
	v_add_u32_e32 v14, 0x1040, v14
	s_waitcnt vmcnt(1)
	ds_write2_b32 v63, v212, v213 offset1:1
	s_waitcnt vmcnt(0)
	ds_write2_b32 v110, v214, v215 offset1:1
	s_lshl_b32 s0, s2, 7
	s_waitcnt lgkmcnt(0)
	s_and_b32 s1, s3, 64
	s_and_b32 s0, s0, 0x3f00
	ds_read2_b32 v[2:3], v81 offset1:65
	s_and_b32 s2, 0xffff, s4
	s_or_b32 s0, s0, s1
	s_waitcnt lgkmcnt(0)
	v_cvt_pk_bf16_f32 v2, v2, v3
	ds_read2_b32 v[4:5], v81 offset0:130 offset1:195
	v_add_u32_e32 v12, 0x400, v81
	s_lshl_b32 s8, s2, 1
	v_or_b32_e32 v10, s0, v80
	s_waitcnt lgkmcnt(0)
	v_cvt_pk_bf16_f32 v3, v4, v5
	ds_read2_b32 v[4:5], v12 offset0:4 offset1:69
	v_lshl_add_u64 v[8:9], v[24:25], 0, s[8:9]
	v_lshlrev_b32_e32 v14, 12, v10
	s_waitcnt lgkmcnt(0)
	v_cvt_pk_bf16_f32 v4, v4, v5
	ds_read2_b32 v[6:7], v12 offset0:134 offset1:199
	s_waitcnt lgkmcnt(0)
	v_cvt_pk_bf16_f32 v5, v6, v7
	v_lshl_add_u64 v[10:11], v[8:9], 0, v[14:15]
	ds_read2_b32 v[6:7], v81 offset0:8 offset1:73
	global_store_dwordx4 v[10:11], v[2:5], off
	v_or_b32_e32 v10, s0, v82
	v_lshlrev_b32_e32 v14, 12, v10
	s_waitcnt lgkmcnt(0)
	v_cvt_pk_bf16_f32 v2, v6, v7
	ds_read2_b32 v[4:5], v81 offset0:138 offset1:203
	s_waitcnt lgkmcnt(0)
	v_cvt_pk_bf16_f32 v3, v4, v5
	ds_read2_b32 v[4:5], v12 offset0:12 offset1:77
	s_waitcnt lgkmcnt(0)
	v_cvt_pk_bf16_f32 v4, v4, v5
	ds_read2_b32 v[6:7], v12 offset0:142 offset1:207
	s_waitcnt lgkmcnt(0)
	v_cvt_pk_bf16_f32 v5, v6, v7
	v_lshl_add_u64 v[10:11], v[8:9], 0, v[14:15]
	ds_read2_b32 v[6:7], v81 offset0:16 offset1:81
	global_store_dwordx4 v[10:11], v[2:5], off
	v_or_b32_e32 v10, s0, v83
	v_lshlrev_b32_e32 v14, 12, v10
	s_waitcnt lgkmcnt(0)
	v_cvt_pk_bf16_f32 v2, v6, v7
	ds_read2_b32 v[4:5], v81 offset0:146 offset1:211
	s_waitcnt lgkmcnt(0)
	v_cvt_pk_bf16_f32 v3, v4, v5
	ds_read2_b32 v[4:5], v12 offset0:20 offset1:85
	s_waitcnt lgkmcnt(0)
	v_cvt_pk_bf16_f32 v4, v4, v5
	ds_read2_b32 v[6:7], v12 offset0:150 offset1:215
	s_waitcnt lgkmcnt(0)
	v_cvt_pk_bf16_f32 v5, v6, v7
	v_lshl_add_u64 v[10:11], v[8:9], 0, v[14:15]
	ds_read2_b32 v[6:7], v81 offset0:24 offset1:89
	global_store_dwordx4 v[10:11], v[2:5], off
	v_or_b32_e32 v10, s0, v84
	v_lshlrev_b32_e32 v14, 12, v10
	s_waitcnt lgkmcnt(0)
	v_cvt_pk_bf16_f32 v2, v6, v7
	ds_read2_b32 v[4:5], v81 offset0:154 offset1:219
	s_waitcnt lgkmcnt(0)
	v_cvt_pk_bf16_f32 v3, v4, v5
	ds_read2_b32 v[4:5], v12 offset0:28 offset1:93
	s_waitcnt lgkmcnt(0)
	v_cvt_pk_bf16_f32 v4, v4, v5
	ds_read2_b32 v[6:7], v12 offset0:158 offset1:223
	s_waitcnt lgkmcnt(0)
	v_cvt_pk_bf16_f32 v5, v6, v7
	v_lshl_add_u64 v[10:11], v[8:9], 0, v[14:15]
	ds_read2_b32 v[6:7], v81 offset0:32 offset1:97
	global_store_dwordx4 v[10:11], v[2:5], off
	v_or_b32_e32 v10, s0, v85
	v_lshlrev_b32_e32 v14, 12, v10
	s_waitcnt lgkmcnt(0)
	v_cvt_pk_bf16_f32 v2, v6, v7
	ds_read2_b32 v[4:5], v81 offset0:162 offset1:227
	s_waitcnt lgkmcnt(0)
	v_cvt_pk_bf16_f32 v3, v4, v5
	ds_read2_b32 v[4:5], v12 offset0:36 offset1:101
	s_waitcnt lgkmcnt(0)
	v_cvt_pk_bf16_f32 v4, v4, v5
	ds_read2_b32 v[6:7], v12 offset0:166 offset1:231
	s_waitcnt lgkmcnt(0)
	v_cvt_pk_bf16_f32 v5, v6, v7
	v_lshl_add_u64 v[10:11], v[8:9], 0, v[14:15]
	ds_read2_b32 v[6:7], v81 offset0:40 offset1:105
	global_store_dwordx4 v[10:11], v[2:5], off
	v_or_b32_e32 v10, s0, v86
	v_lshlrev_b32_e32 v14, 12, v10
	s_waitcnt lgkmcnt(0)
	v_cvt_pk_bf16_f32 v2, v6, v7
	ds_read2_b32 v[4:5], v81 offset0:170 offset1:235
	s_waitcnt lgkmcnt(0)
	v_cvt_pk_bf16_f32 v3, v4, v5
	ds_read2_b32 v[4:5], v12 offset0:44 offset1:109
	s_waitcnt lgkmcnt(0)
	v_cvt_pk_bf16_f32 v4, v4, v5
	ds_read2_b32 v[6:7], v12 offset0:174 offset1:239
	s_waitcnt lgkmcnt(0)
	v_cvt_pk_bf16_f32 v5, v6, v7
	v_lshl_add_u64 v[10:11], v[8:9], 0, v[14:15]
	ds_read2_b32 v[6:7], v81 offset0:48 offset1:113
	global_store_dwordx4 v[10:11], v[2:5], off
	v_or_b32_e32 v10, s0, v87
	v_lshlrev_b32_e32 v14, 12, v10
	s_waitcnt lgkmcnt(0)
	v_cvt_pk_bf16_f32 v2, v6, v7
	ds_read2_b32 v[4:5], v81 offset0:178 offset1:243
	s_waitcnt lgkmcnt(0)
	v_cvt_pk_bf16_f32 v3, v4, v5
	ds_read2_b32 v[4:5], v12 offset0:52 offset1:117
	s_waitcnt lgkmcnt(0)
	v_cvt_pk_bf16_f32 v4, v4, v5
	ds_read2_b32 v[6:7], v12 offset0:182 offset1:247
	s_waitcnt lgkmcnt(0)
	v_cvt_pk_bf16_f32 v5, v6, v7
	v_lshl_add_u64 v[10:11], v[8:9], 0, v[14:15]
	ds_read2_b32 v[6:7], v81 offset0:56 offset1:121
	global_store_dwordx4 v[10:11], v[2:5], off
	s_waitcnt lgkmcnt(0)
	s_nop 0
	v_cvt_pk_bf16_f32 v2, v6, v7
	ds_read2_b32 v[4:5], v81 offset0:186 offset1:251
	s_waitcnt lgkmcnt(0)
	v_cvt_pk_bf16_f32 v3, v4, v5
	ds_read2_b32 v[4:5], v12 offset0:60 offset1:125
	s_waitcnt lgkmcnt(0)
	v_cvt_pk_bf16_f32 v4, v4, v5
	v_or_b32_e32 v5, s0, v88
	ds_read2_b32 v[6:7], v12 offset0:190 offset1:255
	v_lshlrev_b32_e32 v14, 12, v5
	s_waitcnt lgkmcnt(0)
	v_cvt_pk_bf16_f32 v5, v6, v7
	v_lshl_add_u64 v[6:7], v[8:9], 0, v[14:15]
	global_store_dwordx4 v[6:7], v[2:5], off
	s_waitcnt lgkmcnt(0)

.LBB0_50:
	v_add_u32_e32 v5, s1, v62
	v_add_u32_e32 v14, 0xfe520000, v5
	v_lshl_add_u64 v[6:7], v[14:15], 2, v[2:3]
	v_add_u32_e32 v14, 0xfe521000, v5
	v_lshl_add_u64 v[8:9], v[14:15], 2, v[2:3]
	v_add_u32_e32 v14, 0xfe522000, v5
	v_lshl_add_u64 v[10:11], v[14:15], 2, v[2:3]
	v_add_u32_e32 v14, 0xfe523000, v5
	v_lshl_add_u64 v[12:13], v[14:15], 2, v[2:3]
	v_add_u32_e32 v14, 0xfe524000, v5
	v_lshl_add_u64 v[64:65], v[14:15], 2, v[2:3]
	v_add_u32_e32 v14, 0xfe525000, v5
	v_lshl_add_u64 v[66:67], v[14:15], 2, v[2:3]
	v_add_u32_e32 v14, 0xfe526000, v5
	v_lshl_add_u64 v[68:69], v[14:15], 2, v[2:3]
	v_add_u32_e32 v14, 0xfe527000, v5
	global_load_dwordx2 v[6:7], v[6:7], off
	s_nop 0
	global_load_dwordx2 v[8:9], v[8:9], off
	v_lshl_add_u64 v[70:71], v[14:15], 2, v[2:3]
	global_load_dwordx2 v[10:11], v[10:11], off
	s_nop 0
	global_load_dwordx2 v[12:13], v[12:13], off
	s_nop 0
	global_load_dwordx2 v[64:65], v[64:65], off
	s_nop 0
	global_load_dwordx2 v[66:67], v[66:67], off
	s_nop 0
	global_load_dwordx2 v[68:69], v[68:69], off
	s_nop 0
	global_load_dwordx2 v[70:71], v[70:71], off
	s_add_i32 s1, s1, 0x8000
	v_add_u32_e32 v5, s1, v62
	v_add_u32_e32 v14, 0xfe520000, v5
	v_lshl_add_u64 v[200:201], v[14:15], 2, v[2:3]
	v_add_u32_e32 v14, 0xfe521000, v5
	v_lshl_add_u64 v[202:203], v[14:15], 2, v[2:3]
	v_add_u32_e32 v14, 0xfe522000, v5
	v_lshl_add_u64 v[204:205], v[14:15], 2, v[2:3]
	v_add_u32_e32 v14, 0xfe523000, v5
	v_lshl_add_u64 v[206:207], v[14:15], 2, v[2:3]
	v_add_u32_e32 v14, 0xfe524000, v5
	v_lshl_add_u64 v[208:209], v[14:15], 2, v[2:3]
	v_add_u32_e32 v14, 0xfe525000, v5
	v_lshl_add_u64 v[210:211], v[14:15], 2, v[2:3]
	v_add_u32_e32 v14, 0xfe526000, v5
	v_lshl_add_u64 v[212:213], v[14:15], 2, v[2:3]
	v_add_u32_e32 v14, 0xfe527000, v5
	global_load_dwordx2 v[200:201], v[200:201], off
	s_nop 0
	global_load_dwordx2 v[202:203], v[202:203], off
	v_lshl_add_u64 v[214:215], v[14:15], 2, v[2:3]
	global_load_dwordx2 v[204:205], v[204:205], off
	s_nop 0
	global_load_dwordx2 v[206:207], v[206:207], off
	s_nop 0
	global_load_dwordx2 v[208:209], v[208:209], off
	s_nop 0
	global_load_dwordx2 v[210:211], v[210:211], off
	s_nop 0
	global_load_dwordx2 v[212:213], v[212:213], off
	s_nop 0
	global_load_dwordx2 v[214:215], v[214:215], off
	s_add_i32 s1, s1, 0x8000
	v_add_u32_e32 v5, 0x410, v4
	v_add_u32_e32 v14, 0x618, v4
	v_add_u32_e32 v63, 0x820, v4
	v_add_u32_e32 v72, 0xa28, v4
	v_add_u32_e32 v73, 0xc30, v4
	v_add_u32_e32 v74, 0xe38, v4
	s_waitcnt vmcnt(15)
	ds_write2_b32 v4, v6, v7 offset1:1
	s_waitcnt vmcnt(14)
	ds_write2_b32 v4, v8, v9 offset0:130 offset1:131
	v_add_u32_e32 v4, 0x1040, v4
	s_waitcnt vmcnt(13)
	ds_write2_b32 v5, v10, v11 offset1:1
	s_waitcnt vmcnt(12)
	ds_write2_b32 v14, v12, v13 offset1:1
	s_waitcnt vmcnt(11)
	ds_write2_b32 v63, v64, v65 offset1:1
	s_waitcnt vmcnt(10)
	ds_write2_b32 v72, v66, v67 offset1:1
	s_waitcnt vmcnt(9)
	ds_write2_b32 v73, v68, v69 offset1:1
	s_waitcnt vmcnt(8)
	ds_write2_b32 v74, v70, v71 offset1:1
	v_add_u32_e32 v5, s1, v62
	v_add_u32_e32 v14, 0xfe520000, v5
	v_lshl_add_u64 v[6:7], v[14:15], 2, v[2:3]
	v_add_u32_e32 v14, 0xfe521000, v5
	v_lshl_add_u64 v[8:9], v[14:15], 2, v[2:3]
	v_add_u32_e32 v14, 0xfe522000, v5
	v_lshl_add_u64 v[10:11], v[14:15], 2, v[2:3]
	v_add_u32_e32 v14, 0xfe523000, v5
	v_lshl_add_u64 v[12:13], v[14:15], 2, v[2:3]
	v_add_u32_e32 v14, 0xfe524000, v5
	v_lshl_add_u64 v[64:65], v[14:15], 2, v[2:3]
	v_add_u32_e32 v14, 0xfe525000, v5
	v_lshl_add_u64 v[66:67], v[14:15], 2, v[2:3]
	v_add_u32_e32 v14, 0xfe526000, v5
	v_lshl_add_u64 v[68:69], v[14:15], 2, v[2:3]
	v_add_u32_e32 v14, 0xfe527000, v5
	global_load_dwordx2 v[6:7], v[6:7], off
	s_nop 0
	global_load_dwordx2 v[8:9], v[8:9], off
	v_lshl_add_u64 v[70:71], v[14:15], 2, v[2:3]
	global_load_dwordx2 v[10:11], v[10:11], off
	s_nop 0
	global_load_dwordx2 v[12:13], v[12:13], off
	s_nop 0
	global_load_dwordx2 v[64:65], v[64:65], off
	s_nop 0
	global_load_dwordx2 v[66:67], v[66:67], off
	s_nop 0
	global_load_dwordx2 v[68:69], v[68:69], off
	s_nop 0
	global_load_dwordx2 v[70:71], v[70:71], off
	s_add_i32 s1, s1, 0x8000
	v_add_u32_e32 v5, 0x410, v4
	v_add_u32_e32 v14, 0x618, v4
	v_add_u32_e32 v63, 0x820, v4
	v_add_u32_e32 v72, 0xa28, v4
	v_add_u32_e32 v73, 0xc30, v4
	v_add_u32_e32 v74, 0xe38, v4
	s_waitcnt vmcnt(15)
	ds_write2_b32 v4, v200, v201 offset1:1
	s_waitcnt vmcnt(14)
	ds_write2_b32 v4, v202, v203 offset0:130 offset1:131
	v_add_u32_e32 v4, 0x1040, v4
	s_waitcnt vmcnt(13)
	ds_write2_b32 v5, v204, v205 offset1:1
	s_waitcnt vmcnt(12)
	ds_write2_b32 v14, v206, v207 offset1:1
	s_waitcnt vmcnt(11)
	ds_write2_b32 v63, v208, v209 offset1:1
	s_waitcnt vmcnt(10)
	ds_write2_b32 v72, v210, v211 offset1:1
	s_waitcnt vmcnt(9)
	ds_write2_b32 v73, v212, v213 offset1:1
	s_waitcnt vmcnt(8)
	ds_write2_b32 v74, v214, v215 offset1:1
	v_add_u32_e32 v5, s1, v62
	v_add_u32_e32 v14, 0xfe520000, v5
	v_lshl_add_u64 v[200:201], v[14:15], 2, v[2:3]
	v_add_u32_e32 v14, 0xfe521000, v5
	v_lshl_add_u64 v[202:203], v[14:15], 2, v[2:3]
	v_add_u32_e32 v14, 0xfe522000, v5
	v_lshl_add_u64 v[204:205], v[14:15], 2, v[2:3]
	v_add_u32_e32 v14, 0xfe523000, v5
	v_lshl_add_u64 v[206:207], v[14:15], 2, v[2:3]
	v_add_u32_e32 v14, 0xfe524000, v5
	v_lshl_add_u64 v[208:209], v[14:15], 2, v[2:3]
	v_add_u32_e32 v14, 0xfe525000, v5
	v_lshl_add_u64 v[210:211], v[14:15], 2, v[2:3]
	v_add_u32_e32 v14, 0xfe526000, v5
	v_lshl_add_u64 v[212:213], v[14:15], 2, v[2:3]
	v_add_u32_e32 v14, 0xfe527000, v5
	global_load_dwordx2 v[200:201], v[200:201], off
	s_nop 0
	global_load_dwordx2 v[202:203], v[202:203], off
	v_lshl_add_u64 v[214:215], v[14:15], 2, v[2:3]
	global_load_dwordx2 v[204:205], v[204:205], off
	s_nop 0
	global_load_dwordx2 v[206:207], v[206:207], off
	s_nop 0
	global_load_dwordx2 v[208:209], v[208:209], off
	s_nop 0
	global_load_dwordx2 v[210:211], v[210:211], off
	s_nop 0
	global_load_dwordx2 v[212:213], v[212:213], off
	s_nop 0
	global_load_dwordx2 v[214:215], v[214:215], off
	s_add_i32 s1, s1, 0x8000
	v_add_u32_e32 v5, 0x410, v4
	v_add_u32_e32 v14, 0x618, v4
	v_add_u32_e32 v63, 0x820, v4
	v_add_u32_e32 v72, 0xa28, v4
	v_add_u32_e32 v73, 0xc30, v4
	v_add_u32_e32 v74, 0xe38, v4
	s_waitcnt vmcnt(15)
	ds_write2_b32 v4, v6, v7 offset1:1
	s_waitcnt vmcnt(14)
	ds_write2_b32 v4, v8, v9 offset0:130 offset1:131
	v_add_u32_e32 v4, 0x1040, v4
	s_waitcnt vmcnt(13)
	ds_write2_b32 v5, v10, v11 offset1:1
	s_waitcnt vmcnt(12)
	ds_write2_b32 v14, v12, v13 offset1:1
	s_waitcnt vmcnt(11)
	ds_write2_b32 v63, v64, v65 offset1:1
	s_waitcnt vmcnt(10)
	ds_write2_b32 v72, v66, v67 offset1:1
	s_waitcnt vmcnt(9)
	ds_write2_b32 v73, v68, v69 offset1:1
	s_waitcnt vmcnt(8)
	ds_write2_b32 v74, v70, v71 offset1:1
	v_add_u32_e32 v5, 0x410, v4
	v_add_u32_e32 v14, 0x618, v4
	v_add_u32_e32 v63, 0x820, v4
	v_add_u32_e32 v72, 0xa28, v4
	v_add_u32_e32 v73, 0xc30, v4
	v_add_u32_e32 v74, 0xe38, v4
	s_waitcnt vmcnt(7)
	ds_write2_b32 v4, v200, v201 offset1:1
	s_waitcnt vmcnt(6)
	ds_write2_b32 v4, v202, v203 offset0:130 offset1:131
	v_add_u32_e32 v4, 0x1040, v4
	s_waitcnt vmcnt(5)
	ds_write2_b32 v5, v204, v205 offset1:1
	s_waitcnt vmcnt(4)
	ds_write2_b32 v14, v206, v207 offset1:1
	s_waitcnt vmcnt(3)
	ds_write2_b32 v63, v208, v209 offset1:1
	s_waitcnt vmcnt(2)
	ds_write2_b32 v72, v210, v211 offset1:1
	s_waitcnt vmcnt(1)
	ds_write2_b32 v73, v212, v213 offset1:1
	s_waitcnt vmcnt(0)
	ds_write2_b32 v74, v214, v215 offset1:1
	s_waitcnt lgkmcnt(0)
	ds_read2_b32 v[2:3], v81 offset1:65
	s_waitcnt lgkmcnt(0)
	v_cvt_pk_bf16_f32 v2, v2, v3
	ds_read2_b32 v[4:5], v81 offset0:130 offset1:195
	v_add_u32_e32 v12, 0x400, v81
	s_lshl_b32 s1, s96, 1
	s_waitcnt lgkmcnt(0)
	v_cvt_pk_bf16_f32 v3, v4, v5
	ds_read2_b32 v[4:5], v12 offset0:4 offset1:69
	s_and_b32 s1, s1, 0x3fc0
	s_waitcnt lgkmcnt(0)
	v_cvt_pk_bf16_f32 v4, v4, v5
	v_or_b32_e32 v5, s0, v80
	s_add_i32 s8, s1, 0xffffca40
	v_lshlrev_b32_e32 v14, 12, v5
	v_lshl_add_u64 v[8:9], s[8:9], 1, v[28:29]
	ds_read2_b32 v[6:7], v12 offset0:134 offset1:199
	s_waitcnt lgkmcnt(0)
	v_cvt_pk_bf16_f32 v5, v6, v7
	v_lshl_add_u64 v[10:11], v[8:9], 0, v[14:15]
	ds_read2_b32 v[6:7], v81 offset0:8 offset1:73
	global_store_dwordx4 v[10:11], v[2:5], off
	v_or_b32_e32 v10, s0, v82
	v_lshlrev_b32_e32 v14, 12, v10
	s_waitcnt lgkmcnt(0)
	v_cvt_pk_bf16_f32 v2, v6, v7
	ds_read2_b32 v[4:5], v81 offset0:138 offset1:203
	s_waitcnt lgkmcnt(0)
	v_cvt_pk_bf16_f32 v3, v4, v5
	ds_read2_b32 v[4:5], v12 offset0:12 offset1:77
	s_waitcnt lgkmcnt(0)
	v_cvt_pk_bf16_f32 v4, v4, v5
	ds_read2_b32 v[6:7], v12 offset0:142 offset1:207
	s_waitcnt lgkmcnt(0)
	v_cvt_pk_bf16_f32 v5, v6, v7
	v_lshl_add_u64 v[10:11], v[8:9], 0, v[14:15]
	ds_read2_b32 v[6:7], v81 offset0:16 offset1:81
	global_store_dwordx4 v[10:11], v[2:5], off
	v_or_b32_e32 v10, s0, v83
	v_lshlrev_b32_e32 v14, 12, v10
	s_waitcnt lgkmcnt(0)
	v_cvt_pk_bf16_f32 v2, v6, v7
	ds_read2_b32 v[4:5], v81 offset0:146 offset1:211
	s_waitcnt lgkmcnt(0)
	v_cvt_pk_bf16_f32 v3, v4, v5
	ds_read2_b32 v[4:5], v12 offset0:20 offset1:85
	s_waitcnt lgkmcnt(0)
	v_cvt_pk_bf16_f32 v4, v4, v5
	ds_read2_b32 v[6:7], v12 offset0:150 offset1:215
	s_waitcnt lgkmcnt(0)
	v_cvt_pk_bf16_f32 v5, v6, v7
	v_lshl_add_u64 v[10:11], v[8:9], 0, v[14:15]
	ds_read2_b32 v[6:7], v81 offset0:24 offset1:89
	global_store_dwordx4 v[10:11], v[2:5], off
	v_or_b32_e32 v10, s0, v84
	v_lshlrev_b32_e32 v14, 12, v10
	s_waitcnt lgkmcnt(0)
	v_cvt_pk_bf16_f32 v2, v6, v7
	ds_read2_b32 v[4:5], v81 offset0:154 offset1:219
	s_waitcnt lgkmcnt(0)
	v_cvt_pk_bf16_f32 v3, v4, v5
	ds_read2_b32 v[4:5], v12 offset0:28 offset1:93
	s_waitcnt lgkmcnt(0)
	v_cvt_pk_bf16_f32 v4, v4, v5
	ds_read2_b32 v[6:7], v12 offset0:158 offset1:223
	s_waitcnt lgkmcnt(0)
	v_cvt_pk_bf16_f32 v5, v6, v7
	v_lshl_add_u64 v[10:11], v[8:9], 0, v[14:15]
	ds_read2_b32 v[6:7], v81 offset0:32 offset1:97
	global_store_dwordx4 v[10:11], v[2:5], off
	v_or_b32_e32 v10, s0, v85
	v_lshlrev_b32_e32 v14, 12, v10
	s_waitcnt lgkmcnt(0)
	v_cvt_pk_bf16_f32 v2, v6, v7
	ds_read2_b32 v[4:5], v81 offset0:162 offset1:227
	s_waitcnt lgkmcnt(0)
	v_cvt_pk_bf16_f32 v3, v4, v5
	ds_read2_b32 v[4:5], v12 offset0:36 offset1:101
	s_waitcnt lgkmcnt(0)
	v_cvt_pk_bf16_f32 v4, v4, v5
	ds_read2_b32 v[6:7], v12 offset0:166 offset1:231
	s_waitcnt lgkmcnt(0)
	v_cvt_pk_bf16_f32 v5, v6, v7
	v_lshl_add_u64 v[10:11], v[8:9], 0, v[14:15]
	ds_read2_b32 v[6:7], v81 offset0:40 offset1:105
	global_store_dwordx4 v[10:11], v[2:5], off
	v_or_b32_e32 v10, s0, v86
	v_lshlrev_b32_e32 v14, 12, v10
	s_waitcnt lgkmcnt(0)
	v_cvt_pk_bf16_f32 v2, v6, v7
	ds_read2_b32 v[4:5], v81 offset0:170 offset1:235
	s_waitcnt lgkmcnt(0)
	v_cvt_pk_bf16_f32 v3, v4, v5
	ds_read2_b32 v[4:5], v12 offset0:44 offset1:109
	s_waitcnt lgkmcnt(0)
	v_cvt_pk_bf16_f32 v4, v4, v5
	ds_read2_b32 v[6:7], v12 offset0:174 offset1:239
	s_waitcnt lgkmcnt(0)
	v_cvt_pk_bf16_f32 v5, v6, v7
	v_lshl_add_u64 v[10:11], v[8:9], 0, v[14:15]
	ds_read2_b32 v[6:7], v81 offset0:48 offset1:113
	global_store_dwordx4 v[10:11], v[2:5], off
	v_or_b32_e32 v10, s0, v87
	v_lshlrev_b32_e32 v14, 12, v10
	s_waitcnt lgkmcnt(0)
	v_cvt_pk_bf16_f32 v2, v6, v7
	ds_read2_b32 v[4:5], v81 offset0:178 offset1:243
	s_waitcnt lgkmcnt(0)
	v_cvt_pk_bf16_f32 v3, v4, v5
	ds_read2_b32 v[4:5], v12 offset0:52 offset1:117
	s_waitcnt lgkmcnt(0)
	v_cvt_pk_bf16_f32 v4, v4, v5
	ds_read2_b32 v[6:7], v12 offset0:182 offset1:247
	s_waitcnt lgkmcnt(0)
	v_cvt_pk_bf16_f32 v5, v6, v7
	v_lshl_add_u64 v[10:11], v[8:9], 0, v[14:15]
	ds_read2_b32 v[6:7], v81 offset0:56 offset1:121
	global_store_dwordx4 v[10:11], v[2:5], off
	s_waitcnt lgkmcnt(0)
	s_nop 0
	v_cvt_pk_bf16_f32 v2, v6, v7
	ds_read2_b32 v[4:5], v81 offset0:186 offset1:251
	s_waitcnt lgkmcnt(0)
	v_cvt_pk_bf16_f32 v3, v4, v5
	ds_read2_b32 v[4:5], v12 offset0:60 offset1:125
	s_waitcnt lgkmcnt(0)
	v_cvt_pk_bf16_f32 v4, v4, v5
	v_or_b32_e32 v5, s0, v88
	ds_read2_b32 v[6:7], v12 offset0:190 offset1:255
	v_lshlrev_b32_e32 v14, 12, v5
	s_waitcnt lgkmcnt(0)
	v_cvt_pk_bf16_f32 v5, v6, v7
	v_lshl_add_u64 v[6:7], v[8:9], 0, v[14:15]
	global_store_dwordx4 v[6:7], v[2:5], off
	s_waitcnt lgkmcnt(0)

.LBB0_55:
	v_add_u32_e32 v5, s1, v62
	v_add_u32_e32 v14, 0xfe720000, v5
	v_lshl_add_u64 v[6:7], v[14:15], 2, v[2:3]
	v_add_u32_e32 v14, 0xfe721000, v5
	v_lshl_add_u64 v[8:9], v[14:15], 2, v[2:3]
	v_add_u32_e32 v14, 0xfe722000, v5
	v_lshl_add_u64 v[10:11], v[14:15], 2, v[2:3]
	v_add_u32_e32 v14, 0xfe723000, v5
	v_lshl_add_u64 v[12:13], v[14:15], 2, v[2:3]
	v_add_u32_e32 v14, 0xfe724000, v5
	v_lshl_add_u64 v[64:65], v[14:15], 2, v[2:3]
	v_add_u32_e32 v14, 0xfe725000, v5
	v_lshl_add_u64 v[66:67], v[14:15], 2, v[2:3]
	v_add_u32_e32 v14, 0xfe726000, v5
	v_lshl_add_u64 v[68:69], v[14:15], 2, v[2:3]
	v_add_u32_e32 v14, 0xfe727000, v5
	global_load_dwordx2 v[6:7], v[6:7], off
	s_nop 0
	global_load_dwordx2 v[8:9], v[8:9], off
	v_lshl_add_u64 v[70:71], v[14:15], 2, v[2:3]
	global_load_dwordx2 v[10:11], v[10:11], off
	s_nop 0
	global_load_dwordx2 v[12:13], v[12:13], off
	s_nop 0
	global_load_dwordx2 v[64:65], v[64:65], off
	s_nop 0
	global_load_dwordx2 v[66:67], v[66:67], off
	s_nop 0
	global_load_dwordx2 v[68:69], v[68:69], off
	s_nop 0
	global_load_dwordx2 v[70:71], v[70:71], off
	s_add_i32 s1, s1, 0x8000
	v_add_u32_e32 v5, s1, v62
	v_add_u32_e32 v14, 0xfe720000, v5
	v_lshl_add_u64 v[200:201], v[14:15], 2, v[2:3]
	v_add_u32_e32 v14, 0xfe721000, v5
	v_lshl_add_u64 v[202:203], v[14:15], 2, v[2:3]
	v_add_u32_e32 v14, 0xfe722000, v5
	v_lshl_add_u64 v[204:205], v[14:15], 2, v[2:3]
	v_add_u32_e32 v14, 0xfe723000, v5
	v_lshl_add_u64 v[206:207], v[14:15], 2, v[2:3]
	v_add_u32_e32 v14, 0xfe724000, v5
	v_lshl_add_u64 v[208:209], v[14:15], 2, v[2:3]
	v_add_u32_e32 v14, 0xfe725000, v5
	v_lshl_add_u64 v[210:211], v[14:15], 2, v[2:3]
	v_add_u32_e32 v14, 0xfe726000, v5
	v_lshl_add_u64 v[212:213], v[14:15], 2, v[2:3]
	v_add_u32_e32 v14, 0xfe727000, v5
	global_load_dwordx2 v[200:201], v[200:201], off
	s_nop 0
	global_load_dwordx2 v[202:203], v[202:203], off
	v_lshl_add_u64 v[214:215], v[14:15], 2, v[2:3]
	global_load_dwordx2 v[204:205], v[204:205], off
	s_nop 0
	global_load_dwordx2 v[206:207], v[206:207], off
	s_nop 0
	global_load_dwordx2 v[208:209], v[208:209], off
	s_nop 0
	global_load_dwordx2 v[210:211], v[210:211], off
	s_nop 0
	global_load_dwordx2 v[212:213], v[212:213], off
	s_nop 0
	global_load_dwordx2 v[214:215], v[214:215], off
	s_add_i32 s1, s1, 0x8000
	v_add_u32_e32 v5, 0x410, v4
	v_add_u32_e32 v14, 0x618, v4
	v_add_u32_e32 v63, 0x820, v4
	v_add_u32_e32 v72, 0xa28, v4
	v_add_u32_e32 v73, 0xc30, v4
	v_add_u32_e32 v74, 0xe38, v4
	s_waitcnt vmcnt(15)
	ds_write2_b32 v4, v6, v7 offset1:1
	s_waitcnt vmcnt(14)
	ds_write2_b32 v4, v8, v9 offset0:130 offset1:131
	v_add_u32_e32 v4, 0x1040, v4
	s_waitcnt vmcnt(13)
	ds_write2_b32 v5, v10, v11 offset1:1
	s_waitcnt vmcnt(12)
	ds_write2_b32 v14, v12, v13 offset1:1
	s_waitcnt vmcnt(11)
	ds_write2_b32 v63, v64, v65 offset1:1
	s_waitcnt vmcnt(10)
	ds_write2_b32 v72, v66, v67 offset1:1
	s_waitcnt vmcnt(9)
	ds_write2_b32 v73, v68, v69 offset1:1
	s_waitcnt vmcnt(8)
	ds_write2_b32 v74, v70, v71 offset1:1
	v_add_u32_e32 v5, s1, v62
	v_add_u32_e32 v14, 0xfe720000, v5
	v_lshl_add_u64 v[6:7], v[14:15], 2, v[2:3]
	v_add_u32_e32 v14, 0xfe721000, v5
	v_lshl_add_u64 v[8:9], v[14:15], 2, v[2:3]
	v_add_u32_e32 v14, 0xfe722000, v5
	v_lshl_add_u64 v[10:11], v[14:15], 2, v[2:3]
	v_add_u32_e32 v14, 0xfe723000, v5
	v_lshl_add_u64 v[12:13], v[14:15], 2, v[2:3]
	v_add_u32_e32 v14, 0xfe724000, v5
	v_lshl_add_u64 v[64:65], v[14:15], 2, v[2:3]
	v_add_u32_e32 v14, 0xfe725000, v5
	v_lshl_add_u64 v[66:67], v[14:15], 2, v[2:3]
	v_add_u32_e32 v14, 0xfe726000, v5
	v_lshl_add_u64 v[68:69], v[14:15], 2, v[2:3]
	v_add_u32_e32 v14, 0xfe727000, v5
	global_load_dwordx2 v[6:7], v[6:7], off
	s_nop 0
	global_load_dwordx2 v[8:9], v[8:9], off
	v_lshl_add_u64 v[70:71], v[14:15], 2, v[2:3]
	global_load_dwordx2 v[10:11], v[10:11], off
	s_nop 0
	global_load_dwordx2 v[12:13], v[12:13], off
	s_nop 0
	global_load_dwordx2 v[64:65], v[64:65], off
	s_nop 0
	global_load_dwordx2 v[66:67], v[66:67], off
	s_nop 0
	global_load_dwordx2 v[68:69], v[68:69], off
	s_nop 0
	global_load_dwordx2 v[70:71], v[70:71], off
	s_add_i32 s1, s1, 0x8000
	v_add_u32_e32 v5, 0x410, v4
	v_add_u32_e32 v14, 0x618, v4
	v_add_u32_e32 v63, 0x820, v4
	v_add_u32_e32 v72, 0xa28, v4
	v_add_u32_e32 v73, 0xc30, v4
	v_add_u32_e32 v74, 0xe38, v4
	s_waitcnt vmcnt(15)
	ds_write2_b32 v4, v200, v201 offset1:1
	s_waitcnt vmcnt(14)
	ds_write2_b32 v4, v202, v203 offset0:130 offset1:131
	v_add_u32_e32 v4, 0x1040, v4
	s_waitcnt vmcnt(13)
	ds_write2_b32 v5, v204, v205 offset1:1
	s_waitcnt vmcnt(12)
	ds_write2_b32 v14, v206, v207 offset1:1
	s_waitcnt vmcnt(11)
	ds_write2_b32 v63, v208, v209 offset1:1
	s_waitcnt vmcnt(10)
	ds_write2_b32 v72, v210, v211 offset1:1
	s_waitcnt vmcnt(9)
	ds_write2_b32 v73, v212, v213 offset1:1
	s_waitcnt vmcnt(8)
	ds_write2_b32 v74, v214, v215 offset1:1
	v_add_u32_e32 v5, s1, v62
	v_add_u32_e32 v14, 0xfe720000, v5
	v_lshl_add_u64 v[200:201], v[14:15], 2, v[2:3]
	v_add_u32_e32 v14, 0xfe721000, v5
	v_lshl_add_u64 v[202:203], v[14:15], 2, v[2:3]
	v_add_u32_e32 v14, 0xfe722000, v5
	v_lshl_add_u64 v[204:205], v[14:15], 2, v[2:3]
	v_add_u32_e32 v14, 0xfe723000, v5
	v_lshl_add_u64 v[206:207], v[14:15], 2, v[2:3]
	v_add_u32_e32 v14, 0xfe724000, v5
	v_lshl_add_u64 v[208:209], v[14:15], 2, v[2:3]
	v_add_u32_e32 v14, 0xfe725000, v5
	v_lshl_add_u64 v[210:211], v[14:15], 2, v[2:3]
	v_add_u32_e32 v14, 0xfe726000, v5
	v_lshl_add_u64 v[212:213], v[14:15], 2, v[2:3]
	v_add_u32_e32 v14, 0xfe727000, v5
	global_load_dwordx2 v[200:201], v[200:201], off
	s_nop 0
	global_load_dwordx2 v[202:203], v[202:203], off
	v_lshl_add_u64 v[214:215], v[14:15], 2, v[2:3]
	global_load_dwordx2 v[204:205], v[204:205], off
	s_nop 0
	global_load_dwordx2 v[206:207], v[206:207], off
	s_nop 0
	global_load_dwordx2 v[208:209], v[208:209], off
	s_nop 0
	global_load_dwordx2 v[210:211], v[210:211], off
	s_nop 0
	global_load_dwordx2 v[212:213], v[212:213], off
	s_nop 0
	global_load_dwordx2 v[214:215], v[214:215], off
	s_add_i32 s1, s1, 0x8000
	v_add_u32_e32 v5, 0x410, v4
	v_add_u32_e32 v14, 0x618, v4
	v_add_u32_e32 v63, 0x820, v4
	v_add_u32_e32 v72, 0xa28, v4
	v_add_u32_e32 v73, 0xc30, v4
	v_add_u32_e32 v74, 0xe38, v4
	s_waitcnt vmcnt(15)
	ds_write2_b32 v4, v6, v7 offset1:1
	s_waitcnt vmcnt(14)
	ds_write2_b32 v4, v8, v9 offset0:130 offset1:131
	v_add_u32_e32 v4, 0x1040, v4
	s_waitcnt vmcnt(13)
	ds_write2_b32 v5, v10, v11 offset1:1
	s_waitcnt vmcnt(12)
	ds_write2_b32 v14, v12, v13 offset1:1
	s_waitcnt vmcnt(11)
	ds_write2_b32 v63, v64, v65 offset1:1
	s_waitcnt vmcnt(10)
	ds_write2_b32 v72, v66, v67 offset1:1
	s_waitcnt vmcnt(9)
	ds_write2_b32 v73, v68, v69 offset1:1
	s_waitcnt vmcnt(8)
	ds_write2_b32 v74, v70, v71 offset1:1
	v_add_u32_e32 v5, 0x410, v4
	v_add_u32_e32 v14, 0x618, v4
	v_add_u32_e32 v63, 0x820, v4
	v_add_u32_e32 v72, 0xa28, v4
	v_add_u32_e32 v73, 0xc30, v4
	v_add_u32_e32 v74, 0xe38, v4
	s_waitcnt vmcnt(7)
	ds_write2_b32 v4, v200, v201 offset1:1
	s_waitcnt vmcnt(6)
	ds_write2_b32 v4, v202, v203 offset0:130 offset1:131
	v_add_u32_e32 v4, 0x1040, v4
	s_waitcnt vmcnt(5)
	ds_write2_b32 v5, v204, v205 offset1:1
	s_waitcnt vmcnt(4)
	ds_write2_b32 v14, v206, v207 offset1:1
	s_waitcnt vmcnt(3)
	ds_write2_b32 v63, v208, v209 offset1:1
	s_waitcnt vmcnt(2)
	ds_write2_b32 v72, v210, v211 offset1:1
	s_waitcnt vmcnt(1)
	ds_write2_b32 v73, v212, v213 offset1:1
	s_waitcnt vmcnt(0)
	ds_write2_b32 v74, v214, v215 offset1:1
	s_waitcnt lgkmcnt(0)
	ds_read2_b32 v[2:3], v81 offset1:65
	s_waitcnt lgkmcnt(0)
	v_cvt_pk_bf16_f32 v2, v2, v3
	ds_read2_b32 v[4:5], v81 offset0:130 offset1:195
	v_add_u32_e32 v12, 0x400, v81
	s_lshl_b32 s1, s96, 1
	s_waitcnt lgkmcnt(0)
	v_cvt_pk_bf16_f32 v3, v4, v5
	ds_read2_b32 v[4:5], v12 offset0:4 offset1:69
	s_and_b32 s1, s1, 0x3fc0
	s_waitcnt lgkmcnt(0)
	v_cvt_pk_bf16_f32 v4, v4, v5
	v_or_b32_e32 v5, s0, v80
	s_add_i32 s8, s1, 0xffffce40
	v_lshlrev_b32_e32 v14, 11, v5
	v_lshl_add_u64 v[8:9], s[8:9], 1, v[32:33]
	ds_read2_b32 v[6:7], v12 offset0:134 offset1:199
	s_waitcnt lgkmcnt(0)
	v_cvt_pk_bf16_f32 v5, v6, v7
	v_lshl_add_u64 v[10:11], v[8:9], 0, v[14:15]
	ds_read2_b32 v[6:7], v81 offset0:8 offset1:73
	global_store_dwordx4 v[10:11], v[2:5], off
	v_or_b32_e32 v10, s0, v82
	v_lshlrev_b32_e32 v14, 11, v10
	s_waitcnt lgkmcnt(0)
	v_cvt_pk_bf16_f32 v2, v6, v7
	ds_read2_b32 v[4:5], v81 offset0:138 offset1:203
	s_waitcnt lgkmcnt(0)
	v_cvt_pk_bf16_f32 v3, v4, v5
	ds_read2_b32 v[4:5], v12 offset0:12 offset1:77
	s_waitcnt lgkmcnt(0)
	v_cvt_pk_bf16_f32 v4, v4, v5
	ds_read2_b32 v[6:7], v12 offset0:142 offset1:207
	s_waitcnt lgkmcnt(0)
	v_cvt_pk_bf16_f32 v5, v6, v7
	v_lshl_add_u64 v[10:11], v[8:9], 0, v[14:15]
	ds_read2_b32 v[6:7], v81 offset0:16 offset1:81
	global_store_dwordx4 v[10:11], v[2:5], off
	v_or_b32_e32 v10, s0, v83
	v_lshlrev_b32_e32 v14, 11, v10
	s_waitcnt lgkmcnt(0)
	v_cvt_pk_bf16_f32 v2, v6, v7
	ds_read2_b32 v[4:5], v81 offset0:146 offset1:211
	s_waitcnt lgkmcnt(0)
	v_cvt_pk_bf16_f32 v3, v4, v5
	ds_read2_b32 v[4:5], v12 offset0:20 offset1:85
	s_waitcnt lgkmcnt(0)
	v_cvt_pk_bf16_f32 v4, v4, v5
	ds_read2_b32 v[6:7], v12 offset0:150 offset1:215
	s_waitcnt lgkmcnt(0)
	v_cvt_pk_bf16_f32 v5, v6, v7
	v_lshl_add_u64 v[10:11], v[8:9], 0, v[14:15]
	ds_read2_b32 v[6:7], v81 offset0:24 offset1:89
	global_store_dwordx4 v[10:11], v[2:5], off
	v_or_b32_e32 v10, s0, v84
	v_lshlrev_b32_e32 v14, 11, v10
	s_waitcnt lgkmcnt(0)
	v_cvt_pk_bf16_f32 v2, v6, v7
	ds_read2_b32 v[4:5], v81 offset0:154 offset1:219
	s_waitcnt lgkmcnt(0)
	v_cvt_pk_bf16_f32 v3, v4, v5
	ds_read2_b32 v[4:5], v12 offset0:28 offset1:93
	s_waitcnt lgkmcnt(0)
	v_cvt_pk_bf16_f32 v4, v4, v5
	ds_read2_b32 v[6:7], v12 offset0:158 offset1:223
	s_waitcnt lgkmcnt(0)
	v_cvt_pk_bf16_f32 v5, v6, v7
	v_lshl_add_u64 v[10:11], v[8:9], 0, v[14:15]
	ds_read2_b32 v[6:7], v81 offset0:32 offset1:97
	global_store_dwordx4 v[10:11], v[2:5], off
	v_or_b32_e32 v10, s0, v85
	v_lshlrev_b32_e32 v14, 11, v10
	s_waitcnt lgkmcnt(0)
	v_cvt_pk_bf16_f32 v2, v6, v7
	ds_read2_b32 v[4:5], v81 offset0:162 offset1:227
	s_waitcnt lgkmcnt(0)
	v_cvt_pk_bf16_f32 v3, v4, v5
	ds_read2_b32 v[4:5], v12 offset0:36 offset1:101
	s_waitcnt lgkmcnt(0)
	v_cvt_pk_bf16_f32 v4, v4, v5
	ds_read2_b32 v[6:7], v12 offset0:166 offset1:231
	s_waitcnt lgkmcnt(0)
	v_cvt_pk_bf16_f32 v5, v6, v7
	v_lshl_add_u64 v[10:11], v[8:9], 0, v[14:15]
	ds_read2_b32 v[6:7], v81 offset0:40 offset1:105
	global_store_dwordx4 v[10:11], v[2:5], off
	v_or_b32_e32 v10, s0, v86
	v_lshlrev_b32_e32 v14, 11, v10
	s_waitcnt lgkmcnt(0)
	v_cvt_pk_bf16_f32 v2, v6, v7
	ds_read2_b32 v[4:5], v81 offset0:170 offset1:235
	s_waitcnt lgkmcnt(0)
	v_cvt_pk_bf16_f32 v3, v4, v5
	ds_read2_b32 v[4:5], v12 offset0:44 offset1:109
	s_waitcnt lgkmcnt(0)
	v_cvt_pk_bf16_f32 v4, v4, v5
	ds_read2_b32 v[6:7], v12 offset0:174 offset1:239
	s_waitcnt lgkmcnt(0)
	v_cvt_pk_bf16_f32 v5, v6, v7
	v_lshl_add_u64 v[10:11], v[8:9], 0, v[14:15]
	ds_read2_b32 v[6:7], v81 offset0:48 offset1:113
	global_store_dwordx4 v[10:11], v[2:5], off
	v_or_b32_e32 v10, s0, v87
	v_lshlrev_b32_e32 v14, 11, v10
	s_waitcnt lgkmcnt(0)
	v_cvt_pk_bf16_f32 v2, v6, v7
	ds_read2_b32 v[4:5], v81 offset0:178 offset1:243
	s_waitcnt lgkmcnt(0)
	v_cvt_pk_bf16_f32 v3, v4, v5
	ds_read2_b32 v[4:5], v12 offset0:52 offset1:117
	s_waitcnt lgkmcnt(0)
	v_cvt_pk_bf16_f32 v4, v4, v5
	ds_read2_b32 v[6:7], v12 offset0:182 offset1:247
	s_waitcnt lgkmcnt(0)
	v_cvt_pk_bf16_f32 v5, v6, v7
	v_lshl_add_u64 v[10:11], v[8:9], 0, v[14:15]
	ds_read2_b32 v[6:7], v81 offset0:56 offset1:121
	global_store_dwordx4 v[10:11], v[2:5], off
	s_waitcnt lgkmcnt(0)
	s_nop 0
	v_cvt_pk_bf16_f32 v2, v6, v7
	ds_read2_b32 v[4:5], v81 offset0:186 offset1:251
	s_waitcnt lgkmcnt(0)
	v_cvt_pk_bf16_f32 v3, v4, v5
	ds_read2_b32 v[4:5], v12 offset0:60 offset1:125
	s_waitcnt lgkmcnt(0)
	v_cvt_pk_bf16_f32 v4, v4, v5
	v_or_b32_e32 v5, s0, v88
	ds_read2_b32 v[6:7], v12 offset0:190 offset1:255
	v_lshlrev_b32_e32 v14, 11, v5
	s_waitcnt lgkmcnt(0)
	v_cvt_pk_bf16_f32 v5, v6, v7
	v_lshl_add_u64 v[6:7], v[8:9], 0, v[14:15]
	global_store_dwordx4 v[6:7], v[2:5], off
	s_waitcnt lgkmcnt(0)

.LBB0_60:
	v_add_u32_e32 v5, s1, v62
	v_add_u32_e32 v14, 0xfe920000, v5
	v_lshl_add_u64 v[6:7], v[14:15], 2, v[2:3]
	v_add_u32_e32 v14, 0xfe921000, v5
	v_lshl_add_u64 v[8:9], v[14:15], 2, v[2:3]
	v_add_u32_e32 v14, 0xfe922000, v5
	v_lshl_add_u64 v[10:11], v[14:15], 2, v[2:3]
	v_add_u32_e32 v14, 0xfe923000, v5
	v_lshl_add_u64 v[12:13], v[14:15], 2, v[2:3]
	v_add_u32_e32 v14, 0xfe924000, v5
	v_lshl_add_u64 v[64:65], v[14:15], 2, v[2:3]
	v_add_u32_e32 v14, 0xfe925000, v5
	v_lshl_add_u64 v[66:67], v[14:15], 2, v[2:3]
	v_add_u32_e32 v14, 0xfe926000, v5
	v_lshl_add_u64 v[68:69], v[14:15], 2, v[2:3]
	v_add_u32_e32 v14, 0xfe927000, v5
	global_load_dwordx2 v[6:7], v[6:7], off
	s_nop 0
	global_load_dwordx2 v[8:9], v[8:9], off
	v_lshl_add_u64 v[70:71], v[14:15], 2, v[2:3]
	global_load_dwordx2 v[10:11], v[10:11], off
	s_nop 0
	global_load_dwordx2 v[12:13], v[12:13], off
	s_nop 0
	global_load_dwordx2 v[64:65], v[64:65], off
	s_nop 0
	global_load_dwordx2 v[66:67], v[66:67], off
	s_nop 0
	global_load_dwordx2 v[68:69], v[68:69], off
	s_nop 0
	global_load_dwordx2 v[70:71], v[70:71], off
	s_add_i32 s1, s1, 0x8000
	v_add_u32_e32 v5, s1, v62
	v_add_u32_e32 v14, 0xfe920000, v5
	v_lshl_add_u64 v[200:201], v[14:15], 2, v[2:3]
	v_add_u32_e32 v14, 0xfe921000, v5
	v_lshl_add_u64 v[202:203], v[14:15], 2, v[2:3]
	v_add_u32_e32 v14, 0xfe922000, v5
	v_lshl_add_u64 v[204:205], v[14:15], 2, v[2:3]
	v_add_u32_e32 v14, 0xfe923000, v5
	v_lshl_add_u64 v[206:207], v[14:15], 2, v[2:3]
	v_add_u32_e32 v14, 0xfe924000, v5
	v_lshl_add_u64 v[208:209], v[14:15], 2, v[2:3]
	v_add_u32_e32 v14, 0xfe925000, v5
	v_lshl_add_u64 v[210:211], v[14:15], 2, v[2:3]
	v_add_u32_e32 v14, 0xfe926000, v5
	v_lshl_add_u64 v[212:213], v[14:15], 2, v[2:3]
	v_add_u32_e32 v14, 0xfe927000, v5
	global_load_dwordx2 v[200:201], v[200:201], off
	s_nop 0
	global_load_dwordx2 v[202:203], v[202:203], off
	v_lshl_add_u64 v[214:215], v[14:15], 2, v[2:3]
	global_load_dwordx2 v[204:205], v[204:205], off
	s_nop 0
	global_load_dwordx2 v[206:207], v[206:207], off
	s_nop 0
	global_load_dwordx2 v[208:209], v[208:209], off
	s_nop 0
	global_load_dwordx2 v[210:211], v[210:211], off
	s_nop 0
	global_load_dwordx2 v[212:213], v[212:213], off
	s_nop 0
	global_load_dwordx2 v[214:215], v[214:215], off
	s_add_i32 s1, s1, 0x8000
	v_add_u32_e32 v5, 0x410, v4
	v_add_u32_e32 v14, 0x618, v4
	v_add_u32_e32 v63, 0x820, v4
	v_add_u32_e32 v72, 0xa28, v4
	v_add_u32_e32 v73, 0xc30, v4
	v_add_u32_e32 v74, 0xe38, v4
	s_waitcnt vmcnt(15)
	ds_write2_b32 v4, v6, v7 offset1:1
	s_waitcnt vmcnt(14)
	ds_write2_b32 v4, v8, v9 offset0:130 offset1:131
	v_add_u32_e32 v4, 0x1040, v4
	s_waitcnt vmcnt(13)
	ds_write2_b32 v5, v10, v11 offset1:1
	s_waitcnt vmcnt(12)
	ds_write2_b32 v14, v12, v13 offset1:1
	s_waitcnt vmcnt(11)
	ds_write2_b32 v63, v64, v65 offset1:1
	s_waitcnt vmcnt(10)
	ds_write2_b32 v72, v66, v67 offset1:1
	s_waitcnt vmcnt(9)
	ds_write2_b32 v73, v68, v69 offset1:1
	s_waitcnt vmcnt(8)
	ds_write2_b32 v74, v70, v71 offset1:1
	v_add_u32_e32 v5, s1, v62
	v_add_u32_e32 v14, 0xfe920000, v5
	v_lshl_add_u64 v[6:7], v[14:15], 2, v[2:3]
	v_add_u32_e32 v14, 0xfe921000, v5
	v_lshl_add_u64 v[8:9], v[14:15], 2, v[2:3]
	v_add_u32_e32 v14, 0xfe922000, v5
	v_lshl_add_u64 v[10:11], v[14:15], 2, v[2:3]
	v_add_u32_e32 v14, 0xfe923000, v5
	v_lshl_add_u64 v[12:13], v[14:15], 2, v[2:3]
	v_add_u32_e32 v14, 0xfe924000, v5
	v_lshl_add_u64 v[64:65], v[14:15], 2, v[2:3]
	v_add_u32_e32 v14, 0xfe925000, v5
	v_lshl_add_u64 v[66:67], v[14:15], 2, v[2:3]
	v_add_u32_e32 v14, 0xfe926000, v5
	v_lshl_add_u64 v[68:69], v[14:15], 2, v[2:3]
	v_add_u32_e32 v14, 0xfe927000, v5
	global_load_dwordx2 v[6:7], v[6:7], off
	s_nop 0
	global_load_dwordx2 v[8:9], v[8:9], off
	v_lshl_add_u64 v[70:71], v[14:15], 2, v[2:3]
	global_load_dwordx2 v[10:11], v[10:11], off
	s_nop 0
	global_load_dwordx2 v[12:13], v[12:13], off
	s_nop 0
	global_load_dwordx2 v[64:65], v[64:65], off
	s_nop 0
	global_load_dwordx2 v[66:67], v[66:67], off
	s_nop 0
	global_load_dwordx2 v[68:69], v[68:69], off
	s_nop 0
	global_load_dwordx2 v[70:71], v[70:71], off
	s_add_i32 s1, s1, 0x8000
	v_add_u32_e32 v5, 0x410, v4
	v_add_u32_e32 v14, 0x618, v4
	v_add_u32_e32 v63, 0x820, v4
	v_add_u32_e32 v72, 0xa28, v4
	v_add_u32_e32 v73, 0xc30, v4
	v_add_u32_e32 v74, 0xe38, v4
	s_waitcnt vmcnt(15)
	ds_write2_b32 v4, v200, v201 offset1:1
	s_waitcnt vmcnt(14)
	ds_write2_b32 v4, v202, v203 offset0:130 offset1:131
	v_add_u32_e32 v4, 0x1040, v4
	s_waitcnt vmcnt(13)
	ds_write2_b32 v5, v204, v205 offset1:1
	s_waitcnt vmcnt(12)
	ds_write2_b32 v14, v206, v207 offset1:1
	s_waitcnt vmcnt(11)
	ds_write2_b32 v63, v208, v209 offset1:1
	s_waitcnt vmcnt(10)
	ds_write2_b32 v72, v210, v211 offset1:1
	s_waitcnt vmcnt(9)
	ds_write2_b32 v73, v212, v213 offset1:1
	s_waitcnt vmcnt(8)
	ds_write2_b32 v74, v214, v215 offset1:1
	v_add_u32_e32 v5, s1, v62
	v_add_u32_e32 v14, 0xfe920000, v5
	v_lshl_add_u64 v[200:201], v[14:15], 2, v[2:3]
	v_add_u32_e32 v14, 0xfe921000, v5
	v_lshl_add_u64 v[202:203], v[14:15], 2, v[2:3]
	v_add_u32_e32 v14, 0xfe922000, v5
	v_lshl_add_u64 v[204:205], v[14:15], 2, v[2:3]
	v_add_u32_e32 v14, 0xfe923000, v5
	v_lshl_add_u64 v[206:207], v[14:15], 2, v[2:3]
	v_add_u32_e32 v14, 0xfe924000, v5
	v_lshl_add_u64 v[208:209], v[14:15], 2, v[2:3]
	v_add_u32_e32 v14, 0xfe925000, v5
	v_lshl_add_u64 v[210:211], v[14:15], 2, v[2:3]
	v_add_u32_e32 v14, 0xfe926000, v5
	v_lshl_add_u64 v[212:213], v[14:15], 2, v[2:3]
	v_add_u32_e32 v14, 0xfe927000, v5
	global_load_dwordx2 v[200:201], v[200:201], off
	s_nop 0
	global_load_dwordx2 v[202:203], v[202:203], off
	v_lshl_add_u64 v[214:215], v[14:15], 2, v[2:3]
	global_load_dwordx2 v[204:205], v[204:205], off
	s_nop 0
	global_load_dwordx2 v[206:207], v[206:207], off
	s_nop 0
	global_load_dwordx2 v[208:209], v[208:209], off
	s_nop 0
	global_load_dwordx2 v[210:211], v[210:211], off
	s_nop 0
	global_load_dwordx2 v[212:213], v[212:213], off
	s_nop 0
	global_load_dwordx2 v[214:215], v[214:215], off
	s_add_i32 s1, s1, 0x8000
	v_add_u32_e32 v5, 0x410, v4
	v_add_u32_e32 v14, 0x618, v4
	v_add_u32_e32 v63, 0x820, v4
	v_add_u32_e32 v72, 0xa28, v4
	v_add_u32_e32 v73, 0xc30, v4
	v_add_u32_e32 v74, 0xe38, v4
	s_waitcnt vmcnt(15)
	ds_write2_b32 v4, v6, v7 offset1:1
	s_waitcnt vmcnt(14)
	ds_write2_b32 v4, v8, v9 offset0:130 offset1:131
	v_add_u32_e32 v4, 0x1040, v4
	s_waitcnt vmcnt(13)
	ds_write2_b32 v5, v10, v11 offset1:1
	s_waitcnt vmcnt(12)
	ds_write2_b32 v14, v12, v13 offset1:1
	s_waitcnt vmcnt(11)
	ds_write2_b32 v63, v64, v65 offset1:1
	s_waitcnt vmcnt(10)
	ds_write2_b32 v72, v66, v67 offset1:1
	s_waitcnt vmcnt(9)
	ds_write2_b32 v73, v68, v69 offset1:1
	s_waitcnt vmcnt(8)
	ds_write2_b32 v74, v70, v71 offset1:1
	v_add_u32_e32 v5, 0x410, v4
	v_add_u32_e32 v14, 0x618, v4
	v_add_u32_e32 v63, 0x820, v4
	v_add_u32_e32 v72, 0xa28, v4
	v_add_u32_e32 v73, 0xc30, v4
	v_add_u32_e32 v74, 0xe38, v4
	s_waitcnt vmcnt(7)
	ds_write2_b32 v4, v200, v201 offset1:1
	s_waitcnt vmcnt(6)
	ds_write2_b32 v4, v202, v203 offset0:130 offset1:131
	v_add_u32_e32 v4, 0x1040, v4
	s_waitcnt vmcnt(5)
	ds_write2_b32 v5, v204, v205 offset1:1
	s_waitcnt vmcnt(4)
	ds_write2_b32 v14, v206, v207 offset1:1
	s_waitcnt vmcnt(3)
	ds_write2_b32 v63, v208, v209 offset1:1
	s_waitcnt vmcnt(2)
	ds_write2_b32 v72, v210, v211 offset1:1
	s_waitcnt vmcnt(1)
	ds_write2_b32 v73, v212, v213 offset1:1
	s_waitcnt vmcnt(0)
	ds_write2_b32 v74, v214, v215 offset1:1
	s_waitcnt lgkmcnt(0)
	ds_read2_b32 v[2:3], v81 offset1:65
	s_waitcnt lgkmcnt(0)
	v_cvt_pk_bf16_f32 v2, v2, v3
	ds_read2_b32 v[4:5], v81 offset0:130 offset1:195
	v_add_u32_e32 v12, 0x400, v81
	s_lshl_b32 s1, s96, 1
	s_waitcnt lgkmcnt(0)
	v_cvt_pk_bf16_f32 v3, v4, v5
	ds_read2_b32 v[4:5], v12 offset0:4 offset1:69
	s_and_b32 s1, s1, 0x3fc0
	s_waitcnt lgkmcnt(0)
	v_cvt_pk_bf16_f32 v4, v4, v5
	v_or_b32_e32 v5, s0, v80
	s_add_i32 s8, s1, 0xffffd240
	v_lshlrev_b32_e32 v14, 11, v5
	v_lshl_add_u64 v[8:9], s[8:9], 1, v[36:37]
	ds_read2_b32 v[6:7], v12 offset0:134 offset1:199
	s_waitcnt lgkmcnt(0)
	v_cvt_pk_bf16_f32 v5, v6, v7
	v_lshl_add_u64 v[10:11], v[8:9], 0, v[14:15]
	ds_read2_b32 v[6:7], v81 offset0:8 offset1:73
	global_store_dwordx4 v[10:11], v[2:5], off
	v_or_b32_e32 v10, s0, v82
	v_lshlrev_b32_e32 v14, 11, v10
	s_waitcnt lgkmcnt(0)
	v_cvt_pk_bf16_f32 v2, v6, v7
	ds_read2_b32 v[4:5], v81 offset0:138 offset1:203
	s_waitcnt lgkmcnt(0)
	v_cvt_pk_bf16_f32 v3, v4, v5
	ds_read2_b32 v[4:5], v12 offset0:12 offset1:77
	s_waitcnt lgkmcnt(0)
	v_cvt_pk_bf16_f32 v4, v4, v5
	ds_read2_b32 v[6:7], v12 offset0:142 offset1:207
	s_waitcnt lgkmcnt(0)
	v_cvt_pk_bf16_f32 v5, v6, v7
	v_lshl_add_u64 v[10:11], v[8:9], 0, v[14:15]
	ds_read2_b32 v[6:7], v81 offset0:16 offset1:81
	global_store_dwordx4 v[10:11], v[2:5], off
	v_or_b32_e32 v10, s0, v83
	v_lshlrev_b32_e32 v14, 11, v10
	s_waitcnt lgkmcnt(0)
	v_cvt_pk_bf16_f32 v2, v6, v7
	ds_read2_b32 v[4:5], v81 offset0:146 offset1:211
	s_waitcnt lgkmcnt(0)
	v_cvt_pk_bf16_f32 v3, v4, v5
	ds_read2_b32 v[4:5], v12 offset0:20 offset1:85
	s_waitcnt lgkmcnt(0)
	v_cvt_pk_bf16_f32 v4, v4, v5
	ds_read2_b32 v[6:7], v12 offset0:150 offset1:215
	s_waitcnt lgkmcnt(0)
	v_cvt_pk_bf16_f32 v5, v6, v7
	v_lshl_add_u64 v[10:11], v[8:9], 0, v[14:15]
	ds_read2_b32 v[6:7], v81 offset0:24 offset1:89
	global_store_dwordx4 v[10:11], v[2:5], off
	v_or_b32_e32 v10, s0, v84
	v_lshlrev_b32_e32 v14, 11, v10
	s_waitcnt lgkmcnt(0)
	v_cvt_pk_bf16_f32 v2, v6, v7
	ds_read2_b32 v[4:5], v81 offset0:154 offset1:219
	s_waitcnt lgkmcnt(0)
	v_cvt_pk_bf16_f32 v3, v4, v5
	ds_read2_b32 v[4:5], v12 offset0:28 offset1:93
	s_waitcnt lgkmcnt(0)
	v_cvt_pk_bf16_f32 v4, v4, v5
	ds_read2_b32 v[6:7], v12 offset0:158 offset1:223
	s_waitcnt lgkmcnt(0)
	v_cvt_pk_bf16_f32 v5, v6, v7
	v_lshl_add_u64 v[10:11], v[8:9], 0, v[14:15]
	ds_read2_b32 v[6:7], v81 offset0:32 offset1:97
	global_store_dwordx4 v[10:11], v[2:5], off
	v_or_b32_e32 v10, s0, v85
	v_lshlrev_b32_e32 v14, 11, v10
	s_waitcnt lgkmcnt(0)
	v_cvt_pk_bf16_f32 v2, v6, v7
	ds_read2_b32 v[4:5], v81 offset0:162 offset1:227
	s_waitcnt lgkmcnt(0)
	v_cvt_pk_bf16_f32 v3, v4, v5
	ds_read2_b32 v[4:5], v12 offset0:36 offset1:101
	s_waitcnt lgkmcnt(0)
	v_cvt_pk_bf16_f32 v4, v4, v5
	ds_read2_b32 v[6:7], v12 offset0:166 offset1:231
	s_waitcnt lgkmcnt(0)
	v_cvt_pk_bf16_f32 v5, v6, v7
	v_lshl_add_u64 v[10:11], v[8:9], 0, v[14:15]
	ds_read2_b32 v[6:7], v81 offset0:40 offset1:105
	global_store_dwordx4 v[10:11], v[2:5], off
	v_or_b32_e32 v10, s0, v86
	v_lshlrev_b32_e32 v14, 11, v10
	s_waitcnt lgkmcnt(0)
	v_cvt_pk_bf16_f32 v2, v6, v7
	ds_read2_b32 v[4:5], v81 offset0:170 offset1:235
	s_waitcnt lgkmcnt(0)
	v_cvt_pk_bf16_f32 v3, v4, v5
	ds_read2_b32 v[4:5], v12 offset0:44 offset1:109
	s_waitcnt lgkmcnt(0)
	v_cvt_pk_bf16_f32 v4, v4, v5
	ds_read2_b32 v[6:7], v12 offset0:174 offset1:239
	s_waitcnt lgkmcnt(0)
	v_cvt_pk_bf16_f32 v5, v6, v7
	v_lshl_add_u64 v[10:11], v[8:9], 0, v[14:15]
	ds_read2_b32 v[6:7], v81 offset0:48 offset1:113
	global_store_dwordx4 v[10:11], v[2:5], off
	v_or_b32_e32 v10, s0, v87
	v_lshlrev_b32_e32 v14, 11, v10
	s_waitcnt lgkmcnt(0)
	v_cvt_pk_bf16_f32 v2, v6, v7
	ds_read2_b32 v[4:5], v81 offset0:178 offset1:243
	s_waitcnt lgkmcnt(0)
	v_cvt_pk_bf16_f32 v3, v4, v5
	ds_read2_b32 v[4:5], v12 offset0:52 offset1:117
	s_waitcnt lgkmcnt(0)
	v_cvt_pk_bf16_f32 v4, v4, v5
	ds_read2_b32 v[6:7], v12 offset0:182 offset1:247
	s_waitcnt lgkmcnt(0)
	v_cvt_pk_bf16_f32 v5, v6, v7
	v_lshl_add_u64 v[10:11], v[8:9], 0, v[14:15]
	ds_read2_b32 v[6:7], v81 offset0:56 offset1:121
	global_store_dwordx4 v[10:11], v[2:5], off
	s_waitcnt lgkmcnt(0)
	s_nop 0
	v_cvt_pk_bf16_f32 v2, v6, v7
	ds_read2_b32 v[4:5], v81 offset0:186 offset1:251
	s_waitcnt lgkmcnt(0)
	v_cvt_pk_bf16_f32 v3, v4, v5
	ds_read2_b32 v[4:5], v12 offset0:60 offset1:125
	s_waitcnt lgkmcnt(0)
	v_cvt_pk_bf16_f32 v4, v4, v5
	v_or_b32_e32 v5, s0, v88
	ds_read2_b32 v[6:7], v12 offset0:190 offset1:255
	v_lshlrev_b32_e32 v14, 11, v5
	s_waitcnt lgkmcnt(0)
	v_cvt_pk_bf16_f32 v5, v6, v7
	v_lshl_add_u64 v[6:7], v[8:9], 0, v[14:15]
	global_store_dwordx4 v[6:7], v[2:5], off
	s_waitcnt lgkmcnt(0)

.LBB0_107:
	v_lshl_add_u64 v[64:65], v[10:11], 0, s[0:1]
	v_add_co_u32_e32 v74, vcc, 0xf000, v64
	v_lshl_add_u64 v[62:63], v[12:13], 0, s[0:1]
	s_nop 0
	v_addc_co_u32_e32 v75, vcc, 0, v65, vcc
	v_add_co_u32_e32 v76, vcc, 0x1f000, v64
	v_lshl_add_u64 v[66:67], v[8:9], 0, s[0:1]
	s_nop 0
	v_addc_co_u32_e32 v77, vcc, 0, v65, vcc
	v_lshl_add_u64 v[68:69], v[6:7], 0, s[0:1]
	v_lshl_add_u64 v[70:71], v[4:5], 0, s[0:1]
	v_lshl_add_u64 v[72:73], v[2:3], 0, s[0:1]
	v_add_co_u32_e32 v64, vcc, 0x2e000, v64
	global_load_dwordx2 v[62:63], v[62:63], off
	s_nop 0
	global_load_dwordx2 v[66:67], v[66:67], off
	s_nop 0
	global_load_dwordx2 v[68:69], v[68:69], off
	s_nop 0
	global_load_dwordx2 v[70:71], v[70:71], off
	s_nop 0
	global_load_dwordx2 v[72:73], v[72:73], off
	v_addc_co_u32_e32 v65, vcc, 0, v65, vcc
	global_load_dwordx2 v[74:75], v[74:75], off offset:2560
	s_nop 0
	global_load_dwordx2 v[76:77], v[76:77], off offset:1024
	s_nop 0
	global_load_dwordx2 v[64:65], v[64:65], off offset:3584
	s_add_u32 s0, s0, 0x7d000
	s_addc_u32 s1, s1, 0
	v_lshl_add_u64 v[214:215], v[10:11], 0, s[0:1]
	v_add_co_u32_e32 v210, vcc, 0xf000, v214
	v_lshl_add_u64 v[200:201], v[12:13], 0, s[0:1]
	s_nop 0
	v_addc_co_u32_e32 v211, vcc, 0, v215, vcc
	v_add_co_u32_e32 v212, vcc, 0x1f000, v214
	v_lshl_add_u64 v[202:203], v[8:9], 0, s[0:1]
	s_nop 0
	v_addc_co_u32_e32 v213, vcc, 0, v215, vcc
	v_lshl_add_u64 v[204:205], v[6:7], 0, s[0:1]
	v_lshl_add_u64 v[206:207], v[4:5], 0, s[0:1]
	v_lshl_add_u64 v[208:209], v[2:3], 0, s[0:1]
	v_add_co_u32_e32 v214, vcc, 0x2e000, v214
	global_load_dwordx2 v[200:201], v[200:201], off
	s_nop 0
	global_load_dwordx2 v[202:203], v[202:203], off
	s_nop 0
	global_load_dwordx2 v[204:205], v[204:205], off
	s_nop 0
	global_load_dwordx2 v[206:207], v[206:207], off
	s_nop 0
	global_load_dwordx2 v[208:209], v[208:209], off
	v_addc_co_u32_e32 v215, vcc, 0, v215, vcc
	global_load_dwordx2 v[210:211], v[210:211], off offset:2560
	s_nop 0
	global_load_dwordx2 v[212:213], v[212:213], off offset:1024
	s_nop 0
	global_load_dwordx2 v[214:215], v[214:215], off offset:3584
	s_add_u32 s0, s0, 0x7d000
	s_addc_u32 s1, s1, 0
	v_add_u32_e32 v108, 0x410, v14
	v_add_u32_e32 v109, 0x618, v14
	v_add_u32_e32 v110, 0x820, v14
	v_add_u32_e32 v111, 0xa28, v14
	v_add_u32_e32 v112, 0xc30, v14
	v_add_u32_e32 v113, 0xe38, v14
	s_waitcnt vmcnt(15)
	ds_write2_b32 v14, v62, v63 offset1:1
	s_waitcnt vmcnt(14)
	ds_write2_b32 v110, v66, v67 offset1:1
	s_waitcnt vmcnt(13)
	ds_write2_b32 v111, v68, v69 offset1:1
	s_waitcnt vmcnt(12)
	ds_write2_b32 v112, v70, v71 offset1:1
	s_waitcnt vmcnt(11)
	ds_write2_b32 v113, v72, v73 offset1:1
	s_waitcnt vmcnt(10)
	ds_write2_b32 v14, v74, v75 offset0:130 offset1:131
	v_add_u32_e32 v14, 0x1040, v14
	s_waitcnt vmcnt(9)
	ds_write2_b32 v108, v76, v77 offset1:1
	s_waitcnt vmcnt(8)
	ds_write2_b32 v109, v64, v65 offset1:1
	v_lshl_add_u64 v[64:65], v[10:11], 0, s[0:1]
	v_add_co_u32_e32 v74, vcc, 0xf000, v64
	v_lshl_add_u64 v[62:63], v[12:13], 0, s[0:1]
	s_nop 0
	v_addc_co_u32_e32 v75, vcc, 0, v65, vcc
	v_add_co_u32_e32 v76, vcc, 0x1f000, v64
	v_lshl_add_u64 v[66:67], v[8:9], 0, s[0:1]
	s_nop 0
	v_addc_co_u32_e32 v77, vcc, 0, v65, vcc
	v_lshl_add_u64 v[68:69], v[6:7], 0, s[0:1]
	v_lshl_add_u64 v[70:71], v[4:5], 0, s[0:1]
	v_lshl_add_u64 v[72:73], v[2:3], 0, s[0:1]
	v_add_co_u32_e32 v64, vcc, 0x2e000, v64
	global_load_dwordx2 v[62:63], v[62:63], off
	s_nop 0
	global_load_dwordx2 v[66:67], v[66:67], off
	s_nop 0
	global_load_dwordx2 v[68:69], v[68:69], off
	s_nop 0
	global_load_dwordx2 v[70:71], v[70:71], off
	s_nop 0
	global_load_dwordx2 v[72:73], v[72:73], off
	v_addc_co_u32_e32 v65, vcc, 0, v65, vcc
	global_load_dwordx2 v[74:75], v[74:75], off offset:2560
	s_nop 0
	global_load_dwordx2 v[76:77], v[76:77], off offset:1024
	s_nop 0
	global_load_dwordx2 v[64:65], v[64:65], off offset:3584
	s_add_u32 s0, s0, 0x7d000
	s_addc_u32 s1, s1, 0
	v_add_u32_e32 v108, 0x410, v14
	v_add_u32_e32 v109, 0x618, v14
	v_add_u32_e32 v110, 0x820, v14
	v_add_u32_e32 v111, 0xa28, v14
	v_add_u32_e32 v112, 0xc30, v14
	v_add_u32_e32 v113, 0xe38, v14
	s_waitcnt vmcnt(15)
	ds_write2_b32 v14, v200, v201 offset1:1
	s_waitcnt vmcnt(14)
	ds_write2_b32 v110, v202, v203 offset1:1
	s_waitcnt vmcnt(13)
	ds_write2_b32 v111, v204, v205 offset1:1
	s_waitcnt vmcnt(12)
	ds_write2_b32 v112, v206, v207 offset1:1
	s_waitcnt vmcnt(11)
	ds_write2_b32 v113, v208, v209 offset1:1
	s_waitcnt vmcnt(10)
	ds_write2_b32 v14, v210, v211 offset0:130 offset1:131
	v_add_u32_e32 v14, 0x1040, v14
	s_waitcnt vmcnt(9)
	ds_write2_b32 v108, v212, v213 offset1:1
	s_waitcnt vmcnt(8)
	ds_write2_b32 v109, v214, v215 offset1:1
	v_lshl_add_u64 v[214:215], v[10:11], 0, s[0:1]
	v_add_co_u32_e32 v210, vcc, 0xf000, v214
	v_lshl_add_u64 v[200:201], v[12:13], 0, s[0:1]
	s_nop 0
	v_addc_co_u32_e32 v211, vcc, 0, v215, vcc
	v_add_co_u32_e32 v212, vcc, 0x1f000, v214
	v_lshl_add_u64 v[202:203], v[8:9], 0, s[0:1]
	s_nop 0
	v_addc_co_u32_e32 v213, vcc, 0, v215, vcc
	v_lshl_add_u64 v[204:205], v[6:7], 0, s[0:1]
	v_lshl_add_u64 v[206:207], v[4:5], 0, s[0:1]
	v_lshl_add_u64 v[208:209], v[2:3], 0, s[0:1]
	v_add_co_u32_e32 v214, vcc, 0x2e000, v214
	global_load_dwordx2 v[200:201], v[200:201], off
	s_nop 0
	global_load_dwordx2 v[202:203], v[202:203], off
	s_nop 0
	global_load_dwordx2 v[204:205], v[204:205], off
	s_nop 0
	global_load_dwordx2 v[206:207], v[206:207], off
	s_nop 0
	global_load_dwordx2 v[208:209], v[208:209], off
	v_addc_co_u32_e32 v215, vcc, 0, v215, vcc
	global_load_dwordx2 v[210:211], v[210:211], off offset:2560
	s_nop 0
	global_load_dwordx2 v[212:213], v[212:213], off offset:1024
	s_nop 0
	global_load_dwordx2 v[214:215], v[214:215], off offset:3584
	s_add_u32 s0, s0, 0x7d000
	s_addc_u32 s1, s1, 0
	v_add_u32_e32 v108, 0x410, v14
	v_add_u32_e32 v109, 0x618, v14
	v_add_u32_e32 v110, 0x820, v14
	v_add_u32_e32 v111, 0xa28, v14
	v_add_u32_e32 v112, 0xc30, v14
	v_add_u32_e32 v113, 0xe38, v14
	s_waitcnt vmcnt(15)
	ds_write2_b32 v14, v62, v63 offset1:1
	s_waitcnt vmcnt(14)
	ds_write2_b32 v110, v66, v67 offset1:1
	s_waitcnt vmcnt(13)
	ds_write2_b32 v111, v68, v69 offset1:1
	s_waitcnt vmcnt(12)
	ds_write2_b32 v112, v70, v71 offset1:1
	s_waitcnt vmcnt(11)
	ds_write2_b32 v113, v72, v73 offset1:1
	s_waitcnt vmcnt(10)
	ds_write2_b32 v14, v74, v75 offset0:130 offset1:131
	v_add_u32_e32 v14, 0x1040, v14
	s_waitcnt vmcnt(9)
	ds_write2_b32 v108, v76, v77 offset1:1
	s_waitcnt vmcnt(8)
	ds_write2_b32 v109, v64, v65 offset1:1
	v_add_u32_e32 v108, 0x410, v14
	v_add_u32_e32 v109, 0x618, v14
	v_add_u32_e32 v110, 0x820, v14
	v_add_u32_e32 v111, 0xa28, v14
	v_add_u32_e32 v112, 0xc30, v14
	v_add_u32_e32 v113, 0xe38, v14
	s_waitcnt vmcnt(7)
	ds_write2_b32 v14, v200, v201 offset1:1
	s_waitcnt vmcnt(6)
	ds_write2_b32 v110, v202, v203 offset1:1
	s_waitcnt vmcnt(5)
	ds_write2_b32 v111, v204, v205 offset1:1
	s_waitcnt vmcnt(4)
	ds_write2_b32 v112, v206, v207 offset1:1
	s_waitcnt vmcnt(3)
	ds_write2_b32 v113, v208, v209 offset1:1
	s_waitcnt vmcnt(2)
	ds_write2_b32 v14, v210, v211 offset0:130 offset1:131
	v_add_u32_e32 v14, 0x1040, v14
	s_waitcnt vmcnt(1)
	ds_write2_b32 v108, v212, v213 offset1:1
	s_waitcnt vmcnt(0)
	ds_write2_b32 v109, v214, v215 offset1:1
	s_and_b32 s0, 0xffff, s4
	s_cmp_gt_u32 s0, 60
	s_waitcnt lgkmcnt(0)
	s_cselect_b32 s0, 0xc0, 0
	s_and_b32 s1, 0xffff, s3
	ds_read2_b32 v[2:3], v81 offset1:65
	s_and_b32 s2, 0xffff, s2
	s_add_i32 s0, s0, s1
	s_waitcnt lgkmcnt(0)
	v_cvt_pk_bf16_f32 v2, v2, v3
	ds_read2_b32 v[4:5], v81 offset0:130 offset1:195
	v_add_u32_e32 v12, 0x400, v81
	s_lshl_b32 s8, s2, 1
	v_or_b32_e32 v10, s0, v80
	s_waitcnt lgkmcnt(0)
	v_cvt_pk_bf16_f32 v3, v4, v5
	ds_read2_b32 v[4:5], v12 offset0:4 offset1:69
	v_lshl_add_u64 v[8:9], v[44:45], 0, s[8:9]
	v_lshlrev_b32_e32 v14, 12, v10
	s_waitcnt lgkmcnt(0)
	v_cvt_pk_bf16_f32 v4, v4, v5
	ds_read2_b32 v[6:7], v12 offset0:134 offset1:199
	s_waitcnt lgkmcnt(0)
	v_cvt_pk_bf16_f32 v5, v6, v7
	v_lshl_add_u64 v[10:11], v[8:9], 0, v[14:15]
	ds_read2_b32 v[6:7], v81 offset0:8 offset1:73
	global_store_dwordx4 v[10:11], v[2:5], off
	v_or_b32_e32 v10, s0, v82
	v_lshlrev_b32_e32 v14, 12, v10
	s_waitcnt lgkmcnt(0)
	v_cvt_pk_bf16_f32 v2, v6, v7
	ds_read2_b32 v[4:5], v81 offset0:138 offset1:203
	s_waitcnt lgkmcnt(0)
	v_cvt_pk_bf16_f32 v3, v4, v5
	ds_read2_b32 v[4:5], v12 offset0:12 offset1:77
	s_waitcnt lgkmcnt(0)
	v_cvt_pk_bf16_f32 v4, v4, v5
	ds_read2_b32 v[6:7], v12 offset0:142 offset1:207
	s_waitcnt lgkmcnt(0)
	v_cvt_pk_bf16_f32 v5, v6, v7
	v_lshl_add_u64 v[10:11], v[8:9], 0, v[14:15]
	ds_read2_b32 v[6:7], v81 offset0:16 offset1:81
	global_store_dwordx4 v[10:11], v[2:5], off
	v_or_b32_e32 v10, s0, v83
	v_lshlrev_b32_e32 v14, 12, v10
	s_waitcnt lgkmcnt(0)
	v_cvt_pk_bf16_f32 v2, v6, v7
	ds_read2_b32 v[4:5], v81 offset0:146 offset1:211
	s_waitcnt lgkmcnt(0)
	v_cvt_pk_bf16_f32 v3, v4, v5
	ds_read2_b32 v[4:5], v12 offset0:20 offset1:85
	s_waitcnt lgkmcnt(0)
	v_cvt_pk_bf16_f32 v4, v4, v5
	ds_read2_b32 v[6:7], v12 offset0:150 offset1:215
	s_waitcnt lgkmcnt(0)
	v_cvt_pk_bf16_f32 v5, v6, v7
	v_lshl_add_u64 v[10:11], v[8:9], 0, v[14:15]
	ds_read2_b32 v[6:7], v81 offset0:24 offset1:89
	global_store_dwordx4 v[10:11], v[2:5], off
	v_or_b32_e32 v10, s0, v84
	v_lshlrev_b32_e32 v14, 12, v10
	s_waitcnt lgkmcnt(0)
	v_cvt_pk_bf16_f32 v2, v6, v7
	ds_read2_b32 v[4:5], v81 offset0:154 offset1:219
	s_waitcnt lgkmcnt(0)
	v_cvt_pk_bf16_f32 v3, v4, v5
	ds_read2_b32 v[4:5], v12 offset0:28 offset1:93
	s_waitcnt lgkmcnt(0)
	v_cvt_pk_bf16_f32 v4, v4, v5
	ds_read2_b32 v[6:7], v12 offset0:158 offset1:223
	s_waitcnt lgkmcnt(0)
	v_cvt_pk_bf16_f32 v5, v6, v7
	v_lshl_add_u64 v[10:11], v[8:9], 0, v[14:15]
	ds_read2_b32 v[6:7], v81 offset0:32 offset1:97
	global_store_dwordx4 v[10:11], v[2:5], off
	v_or_b32_e32 v10, s0, v85
	v_lshlrev_b32_e32 v14, 12, v10
	s_waitcnt lgkmcnt(0)
	v_cvt_pk_bf16_f32 v2, v6, v7
	ds_read2_b32 v[4:5], v81 offset0:162 offset1:227
	s_waitcnt lgkmcnt(0)
	v_cvt_pk_bf16_f32 v3, v4, v5
	ds_read2_b32 v[4:5], v12 offset0:36 offset1:101
	s_waitcnt lgkmcnt(0)
	v_cvt_pk_bf16_f32 v4, v4, v5
	ds_read2_b32 v[6:7], v12 offset0:166 offset1:231
	s_waitcnt lgkmcnt(0)
	v_cvt_pk_bf16_f32 v5, v6, v7
	v_lshl_add_u64 v[10:11], v[8:9], 0, v[14:15]
	ds_read2_b32 v[6:7], v81 offset0:40 offset1:105
	global_store_dwordx4 v[10:11], v[2:5], off
	v_or_b32_e32 v10, s0, v86
	v_lshlrev_b32_e32 v14, 12, v10
	s_waitcnt lgkmcnt(0)
	v_cvt_pk_bf16_f32 v2, v6, v7
	ds_read2_b32 v[4:5], v81 offset0:170 offset1:235
	s_waitcnt lgkmcnt(0)
	v_cvt_pk_bf16_f32 v3, v4, v5
	ds_read2_b32 v[4:5], v12 offset0:44 offset1:109
	s_waitcnt lgkmcnt(0)
	v_cvt_pk_bf16_f32 v4, v4, v5
	ds_read2_b32 v[6:7], v12 offset0:174 offset1:239
	s_waitcnt lgkmcnt(0)
	v_cvt_pk_bf16_f32 v5, v6, v7
	v_lshl_add_u64 v[10:11], v[8:9], 0, v[14:15]
	ds_read2_b32 v[6:7], v81 offset0:48 offset1:113
	global_store_dwordx4 v[10:11], v[2:5], off
	v_or_b32_e32 v10, s0, v87
	v_lshlrev_b32_e32 v14, 12, v10
	s_waitcnt lgkmcnt(0)
	v_cvt_pk_bf16_f32 v2, v6, v7
	ds_read2_b32 v[4:5], v81 offset0:178 offset1:243
	s_waitcnt lgkmcnt(0)
	v_cvt_pk_bf16_f32 v3, v4, v5
	ds_read2_b32 v[4:5], v12 offset0:52 offset1:117
	s_waitcnt lgkmcnt(0)
	v_cvt_pk_bf16_f32 v4, v4, v5
	ds_read2_b32 v[6:7], v12 offset0:182 offset1:247
	s_waitcnt lgkmcnt(0)
	v_cvt_pk_bf16_f32 v5, v6, v7
	v_lshl_add_u64 v[10:11], v[8:9], 0, v[14:15]
	ds_read2_b32 v[6:7], v81 offset0:56 offset1:121
	global_store_dwordx4 v[10:11], v[2:5], off
	s_waitcnt lgkmcnt(0)
	s_nop 0
	v_cvt_pk_bf16_f32 v2, v6, v7
	ds_read2_b32 v[4:5], v81 offset0:186 offset1:251
	s_waitcnt lgkmcnt(0)
	v_cvt_pk_bf16_f32 v3, v4, v5
	ds_read2_b32 v[4:5], v12 offset0:60 offset1:125
	s_waitcnt lgkmcnt(0)
	v_cvt_pk_bf16_f32 v4, v4, v5
	v_or_b32_e32 v5, s0, v88
	ds_read2_b32 v[6:7], v12 offset0:190 offset1:255
	v_lshlrev_b32_e32 v14, 12, v5
	s_waitcnt lgkmcnt(0)
	v_cvt_pk_bf16_f32 v5, v6, v7
	v_lshl_add_u64 v[6:7], v[8:9], 0, v[14:15]
	global_store_dwordx4 v[6:7], v[2:5], off
	s_waitcnt lgkmcnt(0)
